# big-GEMM K-loops: s_setprio 0 moved behind the post-MFMA barrier (one SALU less on the pre-barrier path of the MFMA-phase half, 4 sites per iteration)
# speedup vs baseline: 1.0048x; 1.0036x over previous
; #define PG8_STAGE(bufoff, gbase, voff) do { _Pragma("unroll") for (int _i = 0; _i < 2; ++_i) \
;         __builtin_amdgcn_global_load_lds((const unsigned*)((const char*)(gbase) + (voff)[_i]), (PG8_LAS unsigned*)(lds + (bufoff) + ldsw + _i * 8192), 16, 0, 0); } while (0)
; #define PG8_LDA(dst, b, h) do { _Pragma("unroll") for (int m = 0; m < 4; ++m) _Pragma("unroll") for (int k = 0; k < 2; ++k) dst[m][k] = *(const PG8_LAS bf16x8*)(lds + PG8_SA(b, h) + aoff + m * 2048 + k * 1024); } while (0)
; #define PG8_LDB(dst, b, h) do { _Pragma("unroll") for (int n = 0; n < 2; ++n) _Pragma("unroll") for (int k = 0; k < 2; ++k) dst[n][k] = *(const PG8_LAS bf16x8*)(lds + PG8_SB(b, h) + boff + n * 2048 + k * 1024); } while (0)
; #define PG8_MMA(ai, bj, At, Bt) do { __builtin_amdgcn_s_setprio(1); _Pragma("unroll") for (int m = 0; m < 4; ++m) _Pragma("unroll") for (int n = 0; n < 2; ++n) _Pragma("unroll") for (int k = 0; k < 2; ++k) \
;         acc[ai][bj][m][n] = __builtin_amdgcn_mfma_f32_16x16x32_bf16(Bt[n][k], At[m][k], acc[ai][bj][m][n], 0, 0, 0); __builtin_amdgcn_s_setprio(0); } while (0)
; #define PG8_WAIT_V(n) asm volatile("s_waitcnt vmcnt(" #n ")" ::: "memory")
; #define PG8_BAR __builtin_amdgcn_s_barrier()
; template <class Epi, class Sched, bool ALIGN_EPI = false, bool SP2 = false>
; __device__ __forceinline__ void gemm_phase(PG8_LAS unsigned char* lds, const Gemm g, const Sched& S, const Epi& E) {
;     ...
;         for (int t = 0; t < nt; t += 2) {
;             const bool last = (t == nt - 2);
;             const char* a1 = cA + (size_t)(t + 1) * kstep;
;             const char* a2 = last ? nA : cA + (size_t)(t + 2) * kstep; const char* b2 = last ? nB : cB + (size_t)(t + 2) * kstep;
;             const char* a3 = a2 + kstep; const char* b3 = b2 + kstep;
;             if (last && has_next) S.a_ready(nxt);
;             if constexpr (SP2) {
;             PG8_LDB(B0, 0, 0); PG8_LDB(B1, 0, 1); PG8_SCHED; PG8_LDA(At, 0, 0); PG8_STAGE(PG8_SA(1, 1), a1 + hstep, voffA);
;             PG8_WAIT_V(8); PG8_WAIT_L(0); PG8_BAR; PG8_MMA(0, 0, At, B0); PG8_MMA(0, 1, At, B1); PG8_BAR; PG8_SCHED;
;             PG8_LDA(At, 0, 1); PG8_STAGE(PG8_SB(0, 0), b2, voffB); PG8_STAGE(PG8_SB(0, 1), b2 + hstep, voffB); PG8_STAGE(PG8_SA(0, 0), a2, voffA);
;             PG8_WAIT_V(8); PG8_WAIT_L(0); PG8_BAR; PG8_MMA(1, 0, At, B0); PG8_MMA(1, 1, At, B1); PG8_BAR; PG8_SCHED;
.LBB0_253:
	ds_read_b128 v[148:151], v161
	ds_read_b128 v[166:169], v161 offset:1024
	ds_read_b128 v[170:173], v161 offset:2048
	ds_read_b128 v[174:177], v161 offset:3072
	ds_read_b128 v[178:181], v162
	ds_read_b128 v[184:187], v162 offset:1024
	ds_read_b128 v[188:191], v162 offset:2048
	ds_read_b128 v[192:195], v162 offset:3072
	s_add_u32 s30, s28, 0xfff80080
	s_addc_u32 s31, s29, -1
	s_cmp_eq_u32 s56, 28
	s_cselect_b32 s35, s3, s31
	s_cselect_b32 s34, s21, s30
	s_cselect_b32 s31, s19, s55
	s_cselect_b32 s30, s27, s54
	v_lshl_add_u64 v[152:153], s[28:29], 0, v[140:141]
	s_add_i32 m0, s38, 0xc000
	ds_read_b128 v[196:199], v163
	ds_read_b128 v[200:203], v163 offset:1024
	ds_read_b128 v[204:207], v163 offset:2048
	ds_read_b128 v[208:211], v163 offset:3072
	ds_read_b128 v[212:215], v163 offset:4096
	ds_read_b128 v[216:219], v163 offset:5120
	ds_read_b128 v[220:223], v163 offset:6144
	ds_read_b128 v[224:227], v163 offset:7168
	global_load_lds_dwordx4 v[152:153], off
	v_lshl_add_u64 v[152:153], s[28:29], 0, v[142:143]
	s_add_i32 m0, s38, 0xe000
	s_nop 0
	global_load_lds_dwordx4 v[152:153], off
	s_waitcnt vmcnt(8)
	s_waitcnt lgkmcnt(0)
	s_barrier
	s_setprio 1
	s_waitcnt lgkmcnt(0)
	v_mfma_f32_16x16x32_bf16 v[124:127], v[148:151], v[196:199], v[124:127]
	v_mfma_f32_16x16x32_bf16 v[120:123], v[170:173], v[196:199], v[120:123]
	v_mfma_f32_16x16x32_bf16 v[116:119], v[148:151], v[204:207], v[116:119]
	v_mfma_f32_16x16x32_bf16 v[112:115], v[170:173], v[204:207], v[112:115]
	v_mfma_f32_16x16x32_bf16 v[108:111], v[148:151], v[212:215], v[108:111]
	v_mfma_f32_16x16x32_bf16 v[104:107], v[170:173], v[212:215], v[104:107]
	v_mfma_f32_16x16x32_bf16 v[100:103], v[148:151], v[220:223], v[100:103]
	v_mfma_f32_16x16x32_bf16 v[96:99], v[170:173], v[220:223], v[96:99]
	v_mfma_f32_16x16x32_bf16 v[124:127], v[166:169], v[200:203], v[124:127]
	v_mfma_f32_16x16x32_bf16 v[120:123], v[174:177], v[200:203], v[120:123]
	v_mfma_f32_16x16x32_bf16 v[116:119], v[166:169], v[208:211], v[116:119]
	v_mfma_f32_16x16x32_bf16 v[112:115], v[174:177], v[208:211], v[112:115]
	v_mfma_f32_16x16x32_bf16 v[108:111], v[166:169], v[216:219], v[108:111]
	v_mfma_f32_16x16x32_bf16 v[104:107], v[174:177], v[216:219], v[104:107]
	v_mfma_f32_16x16x32_bf16 v[100:103], v[166:169], v[224:227], v[100:103]
	v_mfma_f32_16x16x32_bf16 v[96:99], v[174:177], v[224:227], v[96:99]
	s_setprio 0
	s_setprio 1
	v_mfma_f32_16x16x32_bf16 v[92:95], v[178:181], v[196:199], v[92:95]
	v_mfma_f32_16x16x32_bf16 v[88:91], v[188:191], v[196:199], v[88:91]
	v_mfma_f32_16x16x32_bf16 v[84:87], v[178:181], v[204:207], v[84:87]
	v_mfma_f32_16x16x32_bf16 v[80:83], v[188:191], v[204:207], v[80:83]
	v_mfma_f32_16x16x32_bf16 v[76:79], v[178:181], v[212:215], v[76:79]
	v_mfma_f32_16x16x32_bf16 v[72:75], v[188:191], v[212:215], v[72:75]
	v_mfma_f32_16x16x32_bf16 v[68:71], v[178:181], v[220:223], v[68:71]
	v_mfma_f32_16x16x32_bf16 v[64:67], v[188:191], v[220:223], v[64:67]
	v_mfma_f32_16x16x32_bf16 v[92:95], v[184:187], v[200:203], v[92:95]
	v_mfma_f32_16x16x32_bf16 v[88:91], v[192:195], v[200:203], v[88:91]
	v_mfma_f32_16x16x32_bf16 v[84:87], v[184:187], v[208:211], v[84:87]
	v_mfma_f32_16x16x32_bf16 v[80:83], v[192:195], v[208:211], v[80:83]
	v_mfma_f32_16x16x32_bf16 v[76:79], v[184:187], v[216:219], v[76:79]
	v_mfma_f32_16x16x32_bf16 v[72:75], v[192:195], v[216:219], v[72:75]
	v_mfma_f32_16x16x32_bf16 v[68:71], v[184:187], v[224:227], v[68:71]
	v_mfma_f32_16x16x32_bf16 v[64:67], v[192:195], v[224:227], v[64:67]
	s_barrier
	s_setprio 0
	s_add_i32 s57, s48, s37
	v_lshl_add_u64 v[152:153], s[30:31], 0, v[130:131]
	s_mov_b32 m0, s57
	ds_read_b128 v[196:199], v163 offset:16384
	ds_read_b128 v[200:203], v163 offset:17408
	ds_read_b128 v[204:207], v163 offset:18432
	ds_read_b128 v[208:211], v163 offset:19456
	ds_read_b128 v[212:215], v163 offset:20480
	ds_read_b128 v[216:219], v163 offset:21504
	ds_read_b128 v[220:223], v163 offset:22528
	ds_read_b128 v[224:227], v163 offset:23552
	global_load_lds_dwordx4 v[152:153], off
	s_add_i32 m0, s57, 0x2000
	s_add_u32 s58, s30, 0x80000
	v_lshl_add_u64 v[228:229], s[30:31], 0, v[134:135]
	s_addc_u32 s59, s31, 0
	s_add_i32 s57, s49, s37
	global_load_lds_dwordx4 v[228:229], off
	v_lshl_add_u64 v[230:231], s[58:59], 0, v[130:131]
	s_mov_b32 m0, s57
	v_lshl_add_u64 v[232:233], s[34:35], 0, v[132:133]
	global_load_lds_dwordx4 v[230:231], off
	v_lshl_add_u64 v[230:231], s[58:59], 0, v[134:135]
	s_add_i32 m0, s57, 0x2000
	s_nop 0
	global_load_lds_dwordx4 v[230:231], off
	v_lshl_add_u64 v[230:231], s[34:35], 0, v[128:129]
	s_mov_b32 m0, s38
	s_nop 0
	global_load_lds_dwordx4 v[230:231], off
	s_mov_b32 m0, s39
	s_nop 0
	global_load_lds_dwordx4 v[232:233], off
	s_waitcnt vmcnt(8)
	s_waitcnt lgkmcnt(0)
	s_barrier
; #define PG8_STAGE(bufoff, gbase, voff) do { _Pragma("unroll") for (int _i = 0; _i < 2; ++_i) \
;         __builtin_amdgcn_global_load_lds((const unsigned*)((const char*)(gbase) + (voff)[_i]), (PG8_LAS unsigned*)(lds + (bufoff) + ldsw + _i * 8192), 16, 0, 0); } while (0)
; #define PG8_LDA(dst, b, h) do { _Pragma("unroll") for (int m = 0; m < 4; ++m) _Pragma("unroll") for (int k = 0; k < 2; ++k) dst[m][k] = *(const PG8_LAS bf16x8*)(lds + PG8_SA(b, h) + aoff + m * 2048 + k * 1024); } while (0)
; #define PG8_LDB(dst, b, h) do { _Pragma("unroll") for (int n = 0; n < 2; ++n) _Pragma("unroll") for (int k = 0; k < 2; ++k) dst[n][k] = *(const PG8_LAS bf16x8*)(lds + PG8_SB(b, h) + boff + n * 2048 + k * 1024); } while (0)
; #define PG8_MMA(ai, bj, At, Bt) do { __builtin_amdgcn_s_setprio(1); _Pragma("unroll") for (int m = 0; m < 4; ++m) _Pragma("unroll") for (int n = 0; n < 2; ++n) _Pragma("unroll") for (int k = 0; k < 2; ++k) \
;         acc[ai][bj][m][n] = __builtin_amdgcn_mfma_f32_16x16x32_bf16(Bt[n][k], At[m][k], acc[ai][bj][m][n], 0, 0, 0); __builtin_amdgcn_s_setprio(0); } while (0)
; #define PG8_WAIT_V(n) asm volatile("s_waitcnt vmcnt(" #n ")" ::: "memory")
; #define PG8_WAIT_L(n) asm volatile("s_waitcnt lgkmcnt(" #n ")" ::: "memory")
; #define PG8_BAR __builtin_amdgcn_s_barrier()
; #define PG8_SCHED __builtin_amdgcn_sched_barrier(0)
; template <class Epi, class Sched, bool ALIGN_EPI = false, bool SP2 = false>
; __device__ __forceinline__ void gemm_phase(PG8_LAS unsigned char* lds, const Gemm g, const Sched& S, const Epi& E) {
;     ...
;             PG8_WAIT_V(8); PG8_WAIT_L(0); PG8_BAR; PG8_MMA(1, 0, At, B0); PG8_MMA(1, 1, At, B1); PG8_BAR; PG8_SCHED;
;             PG8_LDB(B0, 1, 0); PG8_LDB(B1, 1, 1); PG8_SCHED; PG8_LDA(At, 1, 0); PG8_STAGE(PG8_SA(0, 1), a2 + hstep, voffA);
;             PG8_WAIT_V(8); PG8_WAIT_L(0); PG8_BAR; PG8_MMA(0, 0, At, B0); PG8_MMA(0, 1, At, B1); PG8_BAR; PG8_SCHED;
	s_setprio 1
	s_waitcnt lgkmcnt(0)
	v_mfma_f32_16x16x32_bf16 v[60:63], v[148:151], v[196:199], v[60:63]
	v_mfma_f32_16x16x32_bf16 v[56:59], v[170:173], v[196:199], v[56:59]
	v_mfma_f32_16x16x32_bf16 v[52:55], v[148:151], v[204:207], v[52:55]
	v_mfma_f32_16x16x32_bf16 v[48:51], v[170:173], v[204:207], v[48:51]
	v_mfma_f32_16x16x32_bf16 v[44:47], v[148:151], v[212:215], v[44:47]
	v_mfma_f32_16x16x32_bf16 v[40:43], v[170:173], v[212:215], v[40:43]
	v_mfma_f32_16x16x32_bf16 v[36:39], v[148:151], v[220:223], v[36:39]
	v_mfma_f32_16x16x32_bf16 v[32:35], v[170:173], v[220:223], v[32:35]
	v_mfma_f32_16x16x32_bf16 v[60:63], v[166:169], v[200:203], v[60:63]
	v_mfma_f32_16x16x32_bf16 v[56:59], v[174:177], v[200:203], v[56:59]
	v_mfma_f32_16x16x32_bf16 v[52:55], v[166:169], v[208:211], v[52:55]
	v_mfma_f32_16x16x32_bf16 v[48:51], v[174:177], v[208:211], v[48:51]
	v_mfma_f32_16x16x32_bf16 v[44:47], v[166:169], v[216:219], v[44:47]
	v_mfma_f32_16x16x32_bf16 v[40:43], v[174:177], v[216:219], v[40:43]
	v_mfma_f32_16x16x32_bf16 v[36:39], v[166:169], v[224:227], v[36:39]
	v_mfma_f32_16x16x32_bf16 v[32:35], v[174:177], v[224:227], v[32:35]
	s_setprio 0
	s_setprio 1
	v_mfma_f32_16x16x32_bf16 v[28:31], v[178:181], v[196:199], v[28:31]
	v_mfma_f32_16x16x32_bf16 v[24:27], v[188:191], v[196:199], v[24:27]
	v_mfma_f32_16x16x32_bf16 v[20:23], v[178:181], v[204:207], v[20:23]
	v_mfma_f32_16x16x32_bf16 v[16:19], v[188:191], v[204:207], v[16:19]
	v_mfma_f32_16x16x32_bf16 v[12:15], v[178:181], v[212:215], v[12:15]
	v_mfma_f32_16x16x32_bf16 v[8:11], v[188:191], v[212:215], v[8:11]
	v_mfma_f32_16x16x32_bf16 v[4:7], v[178:181], v[220:223], v[4:7]
	v_mfma_f32_16x16x32_bf16 v[0:3], v[188:191], v[220:223], v[0:3]
	v_mfma_f32_16x16x32_bf16 v[28:31], v[184:187], v[200:203], v[28:31]
	v_mfma_f32_16x16x32_bf16 v[24:27], v[192:195], v[200:203], v[24:27]
	v_mfma_f32_16x16x32_bf16 v[20:23], v[184:187], v[208:211], v[20:23]
	v_mfma_f32_16x16x32_bf16 v[16:19], v[192:195], v[208:211], v[16:19]
	v_mfma_f32_16x16x32_bf16 v[12:15], v[184:187], v[216:219], v[12:15]
	v_mfma_f32_16x16x32_bf16 v[8:11], v[192:195], v[216:219], v[8:11]
	v_mfma_f32_16x16x32_bf16 v[4:7], v[184:187], v[224:227], v[4:7]
	v_mfma_f32_16x16x32_bf16 v[0:3], v[192:195], v[224:227], v[0:3]
	s_barrier
	s_setprio 0
	s_add_i32 s57, 0, 0x18000
	v_add_u32_e32 v136, s57, v159
	s_add_i32 s58, 0, 0x1c000
	ds_read_b128 v[148:151], v136
	ds_read_b128 v[166:169], v136 offset:1024
	ds_read_b128 v[170:173], v136 offset:2048
	ds_read_b128 v[174:177], v136 offset:3072
	v_add_u32_e32 v136, s58, v159
	ds_read_b128 v[178:181], v136
	ds_read_b128 v[184:187], v136 offset:1024
	ds_read_b128 v[188:191], v136 offset:2048
	ds_read_b128 v[192:195], v136 offset:3072
	s_add_u32 s34, s34, 0x80000
	s_addc_u32 s35, s35, 0
	s_mov_b32 m0, s40
	v_lshl_add_u64 v[234:235], s[34:35], 0, v[128:129]
	ds_read_b128 v[196:199], v163 offset:32768
	ds_read_b128 v[200:203], v163 offset:33792
	ds_read_b128 v[204:207], v163 offset:34816
	ds_read_b128 v[208:211], v163 offset:35840
	ds_read_b128 v[212:215], v163 offset:36864
	ds_read_b128 v[216:219], v163 offset:37888
	ds_read_b128 v[220:223], v163 offset:38912
	ds_read_b128 v[224:227], v163 offset:39936
	global_load_lds_dwordx4 v[234:235], off
	v_lshl_add_u64 v[234:235], s[34:35], 0, v[132:133]
	s_mov_b32 m0, s41
	s_nop 0
	global_load_lds_dwordx4 v[234:235], off
	s_waitcnt vmcnt(8)
	s_waitcnt lgkmcnt(0)
	s_barrier
	s_setprio 1
	s_waitcnt lgkmcnt(0)
	v_mfma_f32_16x16x32_bf16 v[124:127], v[148:151], v[196:199], v[124:127]
	v_mfma_f32_16x16x32_bf16 v[120:123], v[170:173], v[196:199], v[120:123]
	v_mfma_f32_16x16x32_bf16 v[116:119], v[148:151], v[204:207], v[116:119]
	v_mfma_f32_16x16x32_bf16 v[112:115], v[170:173], v[204:207], v[112:115]
	v_mfma_f32_16x16x32_bf16 v[108:111], v[148:151], v[212:215], v[108:111]
	v_mfma_f32_16x16x32_bf16 v[104:107], v[170:173], v[212:215], v[104:107]
	v_mfma_f32_16x16x32_bf16 v[100:103], v[148:151], v[220:223], v[100:103]
	v_mfma_f32_16x16x32_bf16 v[96:99], v[170:173], v[220:223], v[96:99]
	v_mfma_f32_16x16x32_bf16 v[124:127], v[166:169], v[200:203], v[124:127]
	v_mfma_f32_16x16x32_bf16 v[120:123], v[174:177], v[200:203], v[120:123]
	v_mfma_f32_16x16x32_bf16 v[116:119], v[166:169], v[208:211], v[116:119]
	v_mfma_f32_16x16x32_bf16 v[112:115], v[174:177], v[208:211], v[112:115]
	v_mfma_f32_16x16x32_bf16 v[108:111], v[166:169], v[216:219], v[108:111]
	v_mfma_f32_16x16x32_bf16 v[104:107], v[174:177], v[216:219], v[104:107]
	v_mfma_f32_16x16x32_bf16 v[100:103], v[166:169], v[224:227], v[100:103]
	v_mfma_f32_16x16x32_bf16 v[96:99], v[174:177], v[224:227], v[96:99]
	s_setprio 0
	s_setprio 1
	v_mfma_f32_16x16x32_bf16 v[92:95], v[178:181], v[196:199], v[92:95]
	v_mfma_f32_16x16x32_bf16 v[88:91], v[188:191], v[196:199], v[88:91]
	v_mfma_f32_16x16x32_bf16 v[84:87], v[178:181], v[204:207], v[84:87]
	v_mfma_f32_16x16x32_bf16 v[80:83], v[188:191], v[204:207], v[80:83]
	v_mfma_f32_16x16x32_bf16 v[76:79], v[178:181], v[212:215], v[76:79]
	v_mfma_f32_16x16x32_bf16 v[72:75], v[188:191], v[212:215], v[72:75]
	v_mfma_f32_16x16x32_bf16 v[68:71], v[178:181], v[220:223], v[68:71]
	v_mfma_f32_16x16x32_bf16 v[64:67], v[188:191], v[220:223], v[64:67]
	v_mfma_f32_16x16x32_bf16 v[92:95], v[184:187], v[200:203], v[92:95]
	v_mfma_f32_16x16x32_bf16 v[88:91], v[192:195], v[200:203], v[88:91]
	v_mfma_f32_16x16x32_bf16 v[84:87], v[184:187], v[208:211], v[84:87]
	v_mfma_f32_16x16x32_bf16 v[80:83], v[192:195], v[208:211], v[80:83]
	v_mfma_f32_16x16x32_bf16 v[76:79], v[184:187], v[216:219], v[76:79]
	v_mfma_f32_16x16x32_bf16 v[72:75], v[192:195], v[216:219], v[72:75]
	v_mfma_f32_16x16x32_bf16 v[68:71], v[184:187], v[224:227], v[68:71]
	v_mfma_f32_16x16x32_bf16 v[64:67], v[192:195], v[224:227], v[64:67]
	s_barrier
; #define PG8_STAGE(bufoff, gbase, voff) do { _Pragma("unroll") for (int _i = 0; _i < 2; ++_i) \
;         __builtin_amdgcn_global_load_lds((const unsigned*)((const char*)(gbase) + (voff)[_i]), (PG8_LAS unsigned*)(lds + (bufoff) + ldsw + _i * 8192), 16, 0, 0); } while (0)
; #define PG8_LDA(dst, b, h) do { _Pragma("unroll") for (int m = 0; m < 4; ++m) _Pragma("unroll") for (int k = 0; k < 2; ++k) dst[m][k] = *(const PG8_LAS bf16x8*)(lds + PG8_SA(b, h) + aoff + m * 2048 + k * 1024); } while (0)
; #define PG8_MMA(ai, bj, At, Bt) do { __builtin_amdgcn_s_setprio(1); _Pragma("unroll") for (int m = 0; m < 4; ++m) _Pragma("unroll") for (int n = 0; n < 2; ++n) _Pragma("unroll") for (int k = 0; k < 2; ++k) \
;         acc[ai][bj][m][n] = __builtin_amdgcn_mfma_f32_16x16x32_bf16(Bt[n][k], At[m][k], acc[ai][bj][m][n], 0, 0, 0); __builtin_amdgcn_s_setprio(0); } while (0)
; #define PG8_WAIT_V(n) asm volatile("s_waitcnt vmcnt(" #n ")" ::: "memory")
; #define PG8_WAIT_L(n) asm volatile("s_waitcnt lgkmcnt(" #n ")" ::: "memory")
; #define PG8_BAR __builtin_amdgcn_s_barrier()
; #define PG8_SCHED __builtin_amdgcn_sched_barrier(0)
; template <class Epi, class Sched, bool ALIGN_EPI = false, bool SP2 = false>
; __device__ __forceinline__ void gemm_phase(PG8_LAS unsigned char* lds, const Gemm g, const Sched& S, const Epi& E) {
;     ...
;             PG8_LDA(At, 1, 1); PG8_STAGE(PG8_SB(1, 0), b3, voffB); PG8_STAGE(PG8_SB(1, 1), b3 + hstep, voffB); PG8_STAGE(PG8_SA(1, 0), a3, voffA);
;             PG8_WAIT_V(8); PG8_WAIT_L(0); PG8_BAR; PG8_MMA(1, 0, At, B0); PG8_MMA(1, 1, At, B1); PG8_BAR; PG8_SCHED;
	s_setprio 0
	s_add_i32 s34, s57, s37
	v_lshl_add_u64 v[152:153], v[152:153], 0, s[14:15]
	s_mov_b32 m0, s34
	ds_read_b128 v[196:199], v163 offset:49152
	ds_read_b128 v[200:203], v163 offset:50176
	ds_read_b128 v[204:207], v163 offset:51200
	ds_read_b128 v[208:211], v163 offset:52224
	ds_read_b128 v[212:215], v163 offset:53248
	ds_read_b128 v[216:219], v163 offset:54272
	ds_read_b128 v[220:223], v163 offset:55296
	ds_read_b128 v[224:227], v163 offset:56320
	global_load_lds_dwordx4 v[152:153], off
	s_add_i32 m0, s34, 0x2000
	s_add_u32 s30, s30, 0x80080
	v_lshl_add_u64 v[152:153], v[228:229], 0, s[14:15]
	s_addc_u32 s31, s31, 0
	s_add_i32 s34, s58, s37
	global_load_lds_dwordx4 v[152:153], off
	v_lshl_add_u64 v[152:153], s[30:31], 0, v[130:131]
	s_mov_b32 m0, s34
	s_nop 0
	global_load_lds_dwordx4 v[152:153], off
	v_lshl_add_u64 v[152:153], s[30:31], 0, v[134:135]
	s_add_i32 m0, s34, 0x2000
	s_nop 0
	global_load_lds_dwordx4 v[152:153], off
	v_lshl_add_u64 v[152:153], v[230:231], 0, s[14:15]
	s_mov_b32 m0, s43
	s_nop 0
	global_load_lds_dwordx4 v[152:153], off
	v_lshl_add_u64 v[152:153], v[232:233], 0, s[14:15]
	s_mov_b32 m0, s44
	s_nop 0
	global_load_lds_dwordx4 v[152:153], off
	s_waitcnt vmcnt(8)
	s_waitcnt lgkmcnt(0)
	s_barrier
	s_setprio 1
	s_waitcnt lgkmcnt(0)
	v_mfma_f32_16x16x32_bf16 v[60:63], v[148:151], v[196:199], v[60:63]
	v_mfma_f32_16x16x32_bf16 v[56:59], v[170:173], v[196:199], v[56:59]
	v_mfma_f32_16x16x32_bf16 v[52:55], v[148:151], v[204:207], v[52:55]
	v_mfma_f32_16x16x32_bf16 v[48:51], v[170:173], v[204:207], v[48:51]
	v_mfma_f32_16x16x32_bf16 v[44:47], v[148:151], v[212:215], v[44:47]
	v_mfma_f32_16x16x32_bf16 v[40:43], v[170:173], v[212:215], v[40:43]
	v_mfma_f32_16x16x32_bf16 v[36:39], v[148:151], v[220:223], v[36:39]
	v_mfma_f32_16x16x32_bf16 v[32:35], v[170:173], v[220:223], v[32:35]
	v_mfma_f32_16x16x32_bf16 v[60:63], v[166:169], v[200:203], v[60:63]
	v_mfma_f32_16x16x32_bf16 v[56:59], v[174:177], v[200:203], v[56:59]
	v_mfma_f32_16x16x32_bf16 v[52:55], v[166:169], v[208:211], v[52:55]
	v_mfma_f32_16x16x32_bf16 v[48:51], v[174:177], v[208:211], v[48:51]
	v_mfma_f32_16x16x32_bf16 v[44:47], v[166:169], v[216:219], v[44:47]
	v_mfma_f32_16x16x32_bf16 v[40:43], v[174:177], v[216:219], v[40:43]
	v_mfma_f32_16x16x32_bf16 v[36:39], v[166:169], v[224:227], v[36:39]
	v_mfma_f32_16x16x32_bf16 v[32:35], v[174:177], v[224:227], v[32:35]
	s_setprio 0
	s_setprio 1
	v_mfma_f32_16x16x32_bf16 v[28:31], v[178:181], v[196:199], v[28:31]
	v_mfma_f32_16x16x32_bf16 v[24:27], v[188:191], v[196:199], v[24:27]
	v_mfma_f32_16x16x32_bf16 v[20:23], v[178:181], v[204:207], v[20:23]
	v_mfma_f32_16x16x32_bf16 v[16:19], v[188:191], v[204:207], v[16:19]
	v_mfma_f32_16x16x32_bf16 v[12:15], v[178:181], v[212:215], v[12:15]
	v_mfma_f32_16x16x32_bf16 v[8:11], v[188:191], v[212:215], v[8:11]
	v_mfma_f32_16x16x32_bf16 v[4:7], v[178:181], v[220:223], v[4:7]
	v_mfma_f32_16x16x32_bf16 v[0:3], v[188:191], v[220:223], v[0:3]
	v_mfma_f32_16x16x32_bf16 v[28:31], v[184:187], v[200:203], v[28:31]
	v_mfma_f32_16x16x32_bf16 v[24:27], v[192:195], v[200:203], v[24:27]
	v_mfma_f32_16x16x32_bf16 v[20:23], v[184:187], v[208:211], v[20:23]
	v_mfma_f32_16x16x32_bf16 v[16:19], v[192:195], v[208:211], v[16:19]
	v_mfma_f32_16x16x32_bf16 v[12:15], v[184:187], v[216:219], v[12:15]
	v_mfma_f32_16x16x32_bf16 v[8:11], v[192:195], v[216:219], v[8:11]
	v_mfma_f32_16x16x32_bf16 v[4:7], v[184:187], v[224:227], v[4:7]
	v_mfma_f32_16x16x32_bf16 v[0:3], v[192:195], v[224:227], v[0:3]
	s_barrier
	s_setprio 0
	s_add_i32 s56, s56, 2
	s_add_u32 s28, s28, 0x100
	s_addc_u32 s29, s29, 0
	s_add_u32 s54, s54, 0x100
	s_addc_u32 s55, s55, 0
	s_cmp_gt_u32 s56, 29
	s_cbranch_scc0 .LBB0_253
	s_and_b64 vcc, exec, s[16:17]
	s_cbranch_vccz .LBB0_256
	s_barrier

; #define PG8_STAGE(bufoff, gbase, voff) do { _Pragma("unroll") for (int _i = 0; _i < 2; ++_i) \
;         __builtin_amdgcn_global_load_lds((const unsigned*)((const char*)(gbase) + (voff)[_i]), (PG8_LAS unsigned*)(lds + (bufoff) + ldsw + _i * 8192), 16, 0, 0); } while (0)
; #define PG8_LDA(dst, b, h) do { _Pragma("unroll") for (int m = 0; m < 4; ++m) _Pragma("unroll") for (int k = 0; k < 2; ++k) dst[m][k] = *(const PG8_LAS bf16x8*)(lds + PG8_SA(b, h) + aoff + m * 2048 + k * 1024); } while (0)
; #define PG8_LDB(dst, b, h) do { _Pragma("unroll") for (int n = 0; n < 2; ++n) _Pragma("unroll") for (int k = 0; k < 2; ++k) dst[n][k] = *(const PG8_LAS bf16x8*)(lds + PG8_SB(b, h) + boff + n * 2048 + k * 1024); } while (0)
; #define PG8_MMA(ai, bj, At, Bt) do { __builtin_amdgcn_s_setprio(1); _Pragma("unroll") for (int m = 0; m < 4; ++m) _Pragma("unroll") for (int n = 0; n < 2; ++n) _Pragma("unroll") for (int k = 0; k < 2; ++k) \
;         acc[ai][bj][m][n] = __builtin_amdgcn_mfma_f32_16x16x32_bf16(Bt[n][k], At[m][k], acc[ai][bj][m][n], 0, 0, 0); __builtin_amdgcn_s_setprio(0); } while (0)
; #define PG8_WAIT_V(n) asm volatile("s_waitcnt vmcnt(" #n ")" ::: "memory")
; #define PG8_WAIT_L(n) asm volatile("s_waitcnt lgkmcnt(" #n ")" ::: "memory")
; #define PG8_BAR __builtin_amdgcn_s_barrier()
; #define PG8_SCHED __builtin_amdgcn_sched_barrier(0)
; template <class Epi, class Sched, bool ALIGN_EPI = false, bool SP2 = false>
; __device__ __forceinline__ void gemm_phase(PG8_LAS unsigned char* lds, const Gemm g, const Sched& S, const Epi& E) {
;     ...
;             const char* a2 = last ? nA : cA + (size_t)(t + 2) * kstep; const char* b2 = last ? nB : cB + (size_t)(t + 2) * kstep;
;             const char* a3 = a2 + kstep; const char* b3 = b2 + kstep;
;             if (last && has_next) S.a_ready(nxt);
;             if constexpr (SP2) {
;             PG8_LDB(B0, 0, 0); PG8_LDB(B1, 0, 1); PG8_SCHED; PG8_LDA(At, 0, 0); PG8_STAGE(PG8_SA(1, 1), a1 + hstep, voffA);
;             PG8_WAIT_V(8); PG8_WAIT_L(0); PG8_BAR; PG8_MMA(0, 0, At, B0); PG8_MMA(0, 1, At, B1); PG8_BAR; PG8_SCHED;
;             PG8_LDA(At, 0, 1); PG8_STAGE(PG8_SB(0, 0), b2, voffB); PG8_STAGE(PG8_SB(0, 1), b2 + hstep, voffB); PG8_STAGE(PG8_SA(0, 0), a2, voffA);
;             PG8_WAIT_V(8); PG8_WAIT_L(0); PG8_BAR; PG8_MMA(1, 0, At, B0); PG8_MMA(1, 1, At, B1); PG8_BAR; PG8_SCHED;
.LBB0_953:
	v_add_u32_e32 v134, s50, v165
	ds_read_b128 v[144:147], v134
	ds_read_b128 v[148:151], v134 offset:1024
	ds_read_b128 v[170:173], v134 offset:2048
	ds_read_b128 v[174:177], v134 offset:3072
	v_add_u32_e32 v134, s51, v165
	ds_read_b128 v[178:181], v134
	ds_read_b128 v[184:187], v134 offset:1024
	ds_read_b128 v[188:191], v134 offset:2048
	ds_read_b128 v[192:195], v134 offset:3072
	s_add_u32 s34, s30, 0xfff80080
	s_addc_u32 s35, s31, -1
	s_cmp_eq_u32 s57, 28
	s_cselect_b32 s37, s21, s35
	s_cselect_b32 s36, s27, s34
	s_cselect_b32 s35, s19, s56
	s_cselect_b32 s34, s54, s55
	v_lshl_add_u64 v[152:153], s[30:31], 0, v[136:137]
	s_add_i32 m0, s29, 0xc000
	ds_read_b128 v[196:199], v167
	ds_read_b128 v[200:203], v167 offset:1024
	ds_read_b128 v[204:207], v167 offset:2048
	ds_read_b128 v[208:211], v167 offset:3072
	ds_read_b128 v[212:215], v167 offset:4096
	ds_read_b128 v[216:219], v167 offset:5120
	ds_read_b128 v[220:223], v167 offset:6144
	ds_read_b128 v[224:227], v167 offset:7168
	global_load_lds_dwordx4 v[152:153], off
	v_lshl_add_u64 v[152:153], s[30:31], 0, v[138:139]
	s_add_i32 m0, s29, 0xe000
	s_nop 0
	global_load_lds_dwordx4 v[152:153], off
	s_waitcnt vmcnt(8)
	s_waitcnt lgkmcnt(0)
	s_barrier
	s_setprio 1
	s_waitcnt lgkmcnt(0)
	v_mfma_f32_16x16x32_bf16 v[124:127], v[144:147], v[196:199], v[124:127]
	v_mfma_f32_16x16x32_bf16 v[120:123], v[170:173], v[196:199], v[120:123]
	v_mfma_f32_16x16x32_bf16 v[116:119], v[144:147], v[204:207], v[116:119]
	v_mfma_f32_16x16x32_bf16 v[112:115], v[170:173], v[204:207], v[112:115]
	v_mfma_f32_16x16x32_bf16 v[108:111], v[144:147], v[212:215], v[108:111]
	v_mfma_f32_16x16x32_bf16 v[104:107], v[170:173], v[212:215], v[104:107]
	v_mfma_f32_16x16x32_bf16 v[100:103], v[144:147], v[220:223], v[100:103]
	v_mfma_f32_16x16x32_bf16 v[96:99], v[170:173], v[220:223], v[96:99]
	v_mfma_f32_16x16x32_bf16 v[124:127], v[148:151], v[200:203], v[124:127]
	v_mfma_f32_16x16x32_bf16 v[120:123], v[174:177], v[200:203], v[120:123]
	v_mfma_f32_16x16x32_bf16 v[116:119], v[148:151], v[208:211], v[116:119]
	v_mfma_f32_16x16x32_bf16 v[112:115], v[174:177], v[208:211], v[112:115]
	v_mfma_f32_16x16x32_bf16 v[108:111], v[148:151], v[216:219], v[108:111]
	v_mfma_f32_16x16x32_bf16 v[104:107], v[174:177], v[216:219], v[104:107]
	v_mfma_f32_16x16x32_bf16 v[100:103], v[148:151], v[224:227], v[100:103]
	v_mfma_f32_16x16x32_bf16 v[96:99], v[174:177], v[224:227], v[96:99]
	s_setprio 0
	s_setprio 1
	v_mfma_f32_16x16x32_bf16 v[92:95], v[178:181], v[196:199], v[92:95]
	v_mfma_f32_16x16x32_bf16 v[88:91], v[188:191], v[196:199], v[88:91]
	v_mfma_f32_16x16x32_bf16 v[84:87], v[178:181], v[204:207], v[84:87]
	v_mfma_f32_16x16x32_bf16 v[80:83], v[188:191], v[204:207], v[80:83]
	v_mfma_f32_16x16x32_bf16 v[76:79], v[178:181], v[212:215], v[76:79]
	v_mfma_f32_16x16x32_bf16 v[72:75], v[188:191], v[212:215], v[72:75]
	v_mfma_f32_16x16x32_bf16 v[68:71], v[178:181], v[220:223], v[68:71]
	v_mfma_f32_16x16x32_bf16 v[64:67], v[188:191], v[220:223], v[64:67]
	v_mfma_f32_16x16x32_bf16 v[92:95], v[184:187], v[200:203], v[92:95]
	v_mfma_f32_16x16x32_bf16 v[88:91], v[192:195], v[200:203], v[88:91]
	v_mfma_f32_16x16x32_bf16 v[84:87], v[184:187], v[208:211], v[84:87]
	v_mfma_f32_16x16x32_bf16 v[80:83], v[192:195], v[208:211], v[80:83]
	v_mfma_f32_16x16x32_bf16 v[76:79], v[184:187], v[216:219], v[76:79]
	v_mfma_f32_16x16x32_bf16 v[72:75], v[192:195], v[216:219], v[72:75]
	v_mfma_f32_16x16x32_bf16 v[68:71], v[184:187], v[224:227], v[68:71]
	v_mfma_f32_16x16x32_bf16 v[64:67], v[192:195], v[224:227], v[64:67]
	s_barrier
	s_setprio 0
	s_add_i32 s58, s50, s41
	v_lshl_add_u64 v[152:153], s[34:35], 0, v[128:129]
	s_mov_b32 m0, s58
	ds_read_b128 v[196:199], v167 offset:16384
	ds_read_b128 v[200:203], v167 offset:17408
	ds_read_b128 v[204:207], v167 offset:18432
	ds_read_b128 v[208:211], v167 offset:19456
	ds_read_b128 v[212:215], v167 offset:20480
	ds_read_b128 v[216:219], v167 offset:21504
	ds_read_b128 v[220:223], v167 offset:22528
	ds_read_b128 v[224:227], v167 offset:23552
	global_load_lds_dwordx4 v[152:153], off
	s_add_i32 m0, s58, 0x2000
	s_add_u32 s58, s34, 0x80000
	v_lshl_add_u64 v[228:229], s[34:35], 0, v[130:131]
	s_addc_u32 s59, s35, 0
	s_add_i32 s60, s51, s41
	global_load_lds_dwordx4 v[228:229], off
	v_lshl_add_u64 v[230:231], s[58:59], 0, v[128:129]
	s_mov_b32 m0, s60
	v_lshl_add_u64 v[232:233], s[36:37], 0, v[130:131]
	global_load_lds_dwordx4 v[230:231], off
	v_lshl_add_u64 v[230:231], s[58:59], 0, v[130:131]
	s_add_i32 m0, s60, 0x2000
	s_nop 0
	global_load_lds_dwordx4 v[230:231], off
	v_lshl_add_u64 v[230:231], s[36:37], 0, v[128:129]
	s_mov_b32 m0, s29
	s_nop 0
	global_load_lds_dwordx4 v[230:231], off
	s_mov_b32 m0, s42
	s_nop 0
	global_load_lds_dwordx4 v[232:233], off
	s_waitcnt vmcnt(8)
	s_waitcnt lgkmcnt(0)
	s_barrier
; #define PG8_STAGE(bufoff, gbase, voff) do { _Pragma("unroll") for (int _i = 0; _i < 2; ++_i) \
;         __builtin_amdgcn_global_load_lds((const unsigned*)((const char*)(gbase) + (voff)[_i]), (PG8_LAS unsigned*)(lds + (bufoff) + ldsw + _i * 8192), 16, 0, 0); } while (0)
; #define PG8_LDA(dst, b, h) do { _Pragma("unroll") for (int m = 0; m < 4; ++m) _Pragma("unroll") for (int k = 0; k < 2; ++k) dst[m][k] = *(const PG8_LAS bf16x8*)(lds + PG8_SA(b, h) + aoff + m * 2048 + k * 1024); } while (0)
; #define PG8_LDB(dst, b, h) do { _Pragma("unroll") for (int n = 0; n < 2; ++n) _Pragma("unroll") for (int k = 0; k < 2; ++k) dst[n][k] = *(const PG8_LAS bf16x8*)(lds + PG8_SB(b, h) + boff + n * 2048 + k * 1024); } while (0)
; #define PG8_MMA(ai, bj, At, Bt) do { __builtin_amdgcn_s_setprio(1); _Pragma("unroll") for (int m = 0; m < 4; ++m) _Pragma("unroll") for (int n = 0; n < 2; ++n) _Pragma("unroll") for (int k = 0; k < 2; ++k) \
;         acc[ai][bj][m][n] = __builtin_amdgcn_mfma_f32_16x16x32_bf16(Bt[n][k], At[m][k], acc[ai][bj][m][n], 0, 0, 0); __builtin_amdgcn_s_setprio(0); } while (0)
; #define PG8_WAIT_V(n) asm volatile("s_waitcnt vmcnt(" #n ")" ::: "memory")
; #define PG8_WAIT_L(n) asm volatile("s_waitcnt lgkmcnt(" #n ")" ::: "memory")
; #define PG8_BAR __builtin_amdgcn_s_barrier()
; #define PG8_SCHED __builtin_amdgcn_sched_barrier(0)
; template <class Epi, class Sched, bool ALIGN_EPI = false, bool SP2 = false>
; __device__ __forceinline__ void gemm_phase(PG8_LAS unsigned char* lds, const Gemm g, const Sched& S, const Epi& E) {
;     ...
;             PG8_WAIT_V(8); PG8_WAIT_L(0); PG8_BAR; PG8_MMA(1, 0, At, B0); PG8_MMA(1, 1, At, B1); PG8_BAR; PG8_SCHED;
;             PG8_LDB(B0, 1, 0); PG8_LDB(B1, 1, 1); PG8_SCHED; PG8_LDA(At, 1, 0); PG8_STAGE(PG8_SA(0, 1), a2 + hstep, voffA);
;             PG8_WAIT_V(8); PG8_WAIT_L(0); PG8_BAR; PG8_MMA(0, 0, At, B0); PG8_MMA(0, 1, At, B1); PG8_BAR; PG8_SCHED;
	s_setprio 1
	s_waitcnt lgkmcnt(0)
	v_mfma_f32_16x16x32_bf16 v[60:63], v[144:147], v[196:199], v[60:63]
	v_mfma_f32_16x16x32_bf16 v[56:59], v[170:173], v[196:199], v[56:59]
	v_mfma_f32_16x16x32_bf16 v[52:55], v[144:147], v[204:207], v[52:55]
	v_mfma_f32_16x16x32_bf16 v[48:51], v[170:173], v[204:207], v[48:51]
	v_mfma_f32_16x16x32_bf16 v[44:47], v[144:147], v[212:215], v[44:47]
	v_mfma_f32_16x16x32_bf16 v[40:43], v[170:173], v[212:215], v[40:43]
	v_mfma_f32_16x16x32_bf16 v[36:39], v[144:147], v[220:223], v[36:39]
	v_mfma_f32_16x16x32_bf16 v[32:35], v[170:173], v[220:223], v[32:35]
	v_mfma_f32_16x16x32_bf16 v[60:63], v[148:151], v[200:203], v[60:63]
	v_mfma_f32_16x16x32_bf16 v[56:59], v[174:177], v[200:203], v[56:59]
	v_mfma_f32_16x16x32_bf16 v[52:55], v[148:151], v[208:211], v[52:55]
	v_mfma_f32_16x16x32_bf16 v[48:51], v[174:177], v[208:211], v[48:51]
	v_mfma_f32_16x16x32_bf16 v[44:47], v[148:151], v[216:219], v[44:47]
	v_mfma_f32_16x16x32_bf16 v[40:43], v[174:177], v[216:219], v[40:43]
	v_mfma_f32_16x16x32_bf16 v[36:39], v[148:151], v[224:227], v[36:39]
	v_mfma_f32_16x16x32_bf16 v[32:35], v[174:177], v[224:227], v[32:35]
	s_setprio 0
	s_setprio 1
	v_mfma_f32_16x16x32_bf16 v[28:31], v[178:181], v[196:199], v[28:31]
	v_mfma_f32_16x16x32_bf16 v[24:27], v[188:191], v[196:199], v[24:27]
	v_mfma_f32_16x16x32_bf16 v[20:23], v[178:181], v[204:207], v[20:23]
	v_mfma_f32_16x16x32_bf16 v[16:19], v[188:191], v[204:207], v[16:19]
	v_mfma_f32_16x16x32_bf16 v[12:15], v[178:181], v[212:215], v[12:15]
	v_mfma_f32_16x16x32_bf16 v[8:11], v[188:191], v[212:215], v[8:11]
	v_mfma_f32_16x16x32_bf16 v[4:7], v[178:181], v[220:223], v[4:7]
	v_mfma_f32_16x16x32_bf16 v[0:3], v[188:191], v[220:223], v[0:3]
	v_mfma_f32_16x16x32_bf16 v[28:31], v[184:187], v[200:203], v[28:31]
	v_mfma_f32_16x16x32_bf16 v[24:27], v[192:195], v[200:203], v[24:27]
	v_mfma_f32_16x16x32_bf16 v[20:23], v[184:187], v[208:211], v[20:23]
	v_mfma_f32_16x16x32_bf16 v[16:19], v[192:195], v[208:211], v[16:19]
	v_mfma_f32_16x16x32_bf16 v[12:15], v[184:187], v[216:219], v[12:15]
	v_mfma_f32_16x16x32_bf16 v[8:11], v[192:195], v[216:219], v[8:11]
	v_mfma_f32_16x16x32_bf16 v[4:7], v[184:187], v[224:227], v[4:7]
	v_mfma_f32_16x16x32_bf16 v[0:3], v[192:195], v[224:227], v[0:3]
	s_barrier
	s_setprio 0
	s_add_i32 s58, 0, 0x18000
	v_add_u32_e32 v134, s58, v165
	s_add_i32 s59, 0, 0x1c000
	ds_read_b128 v[144:147], v134
	ds_read_b128 v[148:151], v134 offset:1024
	ds_read_b128 v[170:173], v134 offset:2048
	ds_read_b128 v[174:177], v134 offset:3072
	v_add_u32_e32 v134, s59, v165
	ds_read_b128 v[178:181], v134
	ds_read_b128 v[184:187], v134 offset:1024
	ds_read_b128 v[188:191], v134 offset:2048
	ds_read_b128 v[192:195], v134 offset:3072
	s_add_u32 s36, s36, 0x80000
	s_addc_u32 s37, s37, 0
	s_mov_b32 m0, s43
	v_lshl_add_u64 v[234:235], s[36:37], 0, v[128:129]
	ds_read_b128 v[196:199], v167 offset:32768
	ds_read_b128 v[200:203], v167 offset:33792
	ds_read_b128 v[204:207], v167 offset:34816
	ds_read_b128 v[208:211], v167 offset:35840
	ds_read_b128 v[212:215], v167 offset:36864
	ds_read_b128 v[216:219], v167 offset:37888
	ds_read_b128 v[220:223], v167 offset:38912
	ds_read_b128 v[224:227], v167 offset:39936
	global_load_lds_dwordx4 v[234:235], off
	v_lshl_add_u64 v[234:235], s[36:37], 0, v[130:131]
	s_mov_b32 m0, s44
	s_nop 0
	global_load_lds_dwordx4 v[234:235], off
	s_waitcnt vmcnt(8)
	s_waitcnt lgkmcnt(0)
	s_barrier
	s_setprio 1
	s_waitcnt lgkmcnt(0)
	v_mfma_f32_16x16x32_bf16 v[124:127], v[144:147], v[196:199], v[124:127]
	v_mfma_f32_16x16x32_bf16 v[120:123], v[170:173], v[196:199], v[120:123]
	v_mfma_f32_16x16x32_bf16 v[116:119], v[144:147], v[204:207], v[116:119]
	v_mfma_f32_16x16x32_bf16 v[112:115], v[170:173], v[204:207], v[112:115]
	v_mfma_f32_16x16x32_bf16 v[108:111], v[144:147], v[212:215], v[108:111]
	v_mfma_f32_16x16x32_bf16 v[104:107], v[170:173], v[212:215], v[104:107]
	v_mfma_f32_16x16x32_bf16 v[100:103], v[144:147], v[220:223], v[100:103]
	v_mfma_f32_16x16x32_bf16 v[96:99], v[170:173], v[220:223], v[96:99]
	v_mfma_f32_16x16x32_bf16 v[124:127], v[148:151], v[200:203], v[124:127]
	v_mfma_f32_16x16x32_bf16 v[120:123], v[174:177], v[200:203], v[120:123]
	v_mfma_f32_16x16x32_bf16 v[116:119], v[148:151], v[208:211], v[116:119]
	v_mfma_f32_16x16x32_bf16 v[112:115], v[174:177], v[208:211], v[112:115]
	v_mfma_f32_16x16x32_bf16 v[108:111], v[148:151], v[216:219], v[108:111]
	v_mfma_f32_16x16x32_bf16 v[104:107], v[174:177], v[216:219], v[104:107]
	v_mfma_f32_16x16x32_bf16 v[100:103], v[148:151], v[224:227], v[100:103]
	v_mfma_f32_16x16x32_bf16 v[96:99], v[174:177], v[224:227], v[96:99]
	s_setprio 0
	s_setprio 1
	v_mfma_f32_16x16x32_bf16 v[92:95], v[178:181], v[196:199], v[92:95]
	v_mfma_f32_16x16x32_bf16 v[88:91], v[188:191], v[196:199], v[88:91]
	v_mfma_f32_16x16x32_bf16 v[84:87], v[178:181], v[204:207], v[84:87]
	v_mfma_f32_16x16x32_bf16 v[80:83], v[188:191], v[204:207], v[80:83]
	v_mfma_f32_16x16x32_bf16 v[76:79], v[178:181], v[212:215], v[76:79]
	v_mfma_f32_16x16x32_bf16 v[72:75], v[188:191], v[212:215], v[72:75]
	v_mfma_f32_16x16x32_bf16 v[68:71], v[178:181], v[220:223], v[68:71]
	v_mfma_f32_16x16x32_bf16 v[64:67], v[188:191], v[220:223], v[64:67]
	v_mfma_f32_16x16x32_bf16 v[92:95], v[184:187], v[200:203], v[92:95]
	v_mfma_f32_16x16x32_bf16 v[88:91], v[192:195], v[200:203], v[88:91]
	v_mfma_f32_16x16x32_bf16 v[84:87], v[184:187], v[208:211], v[84:87]
	v_mfma_f32_16x16x32_bf16 v[80:83], v[192:195], v[208:211], v[80:83]
	v_mfma_f32_16x16x32_bf16 v[76:79], v[184:187], v[216:219], v[76:79]
	v_mfma_f32_16x16x32_bf16 v[72:75], v[192:195], v[216:219], v[72:75]
	v_mfma_f32_16x16x32_bf16 v[68:71], v[184:187], v[224:227], v[68:71]
	v_mfma_f32_16x16x32_bf16 v[64:67], v[192:195], v[224:227], v[64:67]
	s_barrier
; #define PG8_STAGE(bufoff, gbase, voff) do { _Pragma("unroll") for (int _i = 0; _i < 2; ++_i) \
;         __builtin_amdgcn_global_load_lds((const unsigned*)((const char*)(gbase) + (voff)[_i]), (PG8_LAS unsigned*)(lds + (bufoff) + ldsw + _i * 8192), 16, 0, 0); } while (0)
; #define PG8_LDA(dst, b, h) do { _Pragma("unroll") for (int m = 0; m < 4; ++m) _Pragma("unroll") for (int k = 0; k < 2; ++k) dst[m][k] = *(const PG8_LAS bf16x8*)(lds + PG8_SA(b, h) + aoff + m * 2048 + k * 1024); } while (0)
; #define PG8_MMA(ai, bj, At, Bt) do { __builtin_amdgcn_s_setprio(1); _Pragma("unroll") for (int m = 0; m < 4; ++m) _Pragma("unroll") for (int n = 0; n < 2; ++n) _Pragma("unroll") for (int k = 0; k < 2; ++k) \
;         acc[ai][bj][m][n] = __builtin_amdgcn_mfma_f32_16x16x32_bf16(Bt[n][k], At[m][k], acc[ai][bj][m][n], 0, 0, 0); __builtin_amdgcn_s_setprio(0); } while (0)
; #define PG8_WAIT_V(n) asm volatile("s_waitcnt vmcnt(" #n ")" ::: "memory")
; #define PG8_WAIT_L(n) asm volatile("s_waitcnt lgkmcnt(" #n ")" ::: "memory")
; #define PG8_BAR __builtin_amdgcn_s_barrier()
; #define PG8_SCHED __builtin_amdgcn_sched_barrier(0)
; template <class Epi, class Sched, bool ALIGN_EPI = false, bool SP2 = false>
; __device__ __forceinline__ void gemm_phase(PG8_LAS unsigned char* lds, const Gemm g, const Sched& S, const Epi& E) {
;     ...
;             PG8_LDA(At, 1, 1); PG8_STAGE(PG8_SB(1, 0), b3, voffB); PG8_STAGE(PG8_SB(1, 1), b3 + hstep, voffB); PG8_STAGE(PG8_SA(1, 0), a3, voffA);
;             PG8_WAIT_V(8); PG8_WAIT_L(0); PG8_BAR; PG8_MMA(1, 0, At, B0); PG8_MMA(1, 1, At, B1); PG8_BAR; PG8_SCHED;
	s_setprio 0
	s_add_i32 s36, s58, s41
	v_lshl_add_u64 v[152:153], v[152:153], 0, s[14:15]
	s_mov_b32 m0, s36
	ds_read_b128 v[196:199], v167 offset:49152
	ds_read_b128 v[200:203], v167 offset:50176
	ds_read_b128 v[204:207], v167 offset:51200
	ds_read_b128 v[208:211], v167 offset:52224
	ds_read_b128 v[212:215], v167 offset:53248
	ds_read_b128 v[216:219], v167 offset:54272
	ds_read_b128 v[220:223], v167 offset:55296
	ds_read_b128 v[224:227], v167 offset:56320
	global_load_lds_dwordx4 v[152:153], off
	s_add_i32 m0, s36, 0x2000
	s_add_u32 s34, s34, 0x80080
	v_lshl_add_u64 v[152:153], v[228:229], 0, s[14:15]
	s_addc_u32 s35, s35, 0
	s_add_i32 s36, s59, s41
	global_load_lds_dwordx4 v[152:153], off
	v_lshl_add_u64 v[152:153], s[34:35], 0, v[128:129]
	s_mov_b32 m0, s36
	s_nop 0
	global_load_lds_dwordx4 v[152:153], off
	v_lshl_add_u64 v[152:153], s[34:35], 0, v[130:131]
	s_add_i32 m0, s36, 0x2000
	s_nop 0
	global_load_lds_dwordx4 v[152:153], off
	v_lshl_add_u64 v[152:153], v[230:231], 0, s[14:15]
	s_mov_b32 m0, s45
	s_nop 0
	global_load_lds_dwordx4 v[152:153], off
	v_lshl_add_u64 v[152:153], v[232:233], 0, s[14:15]
	s_mov_b32 m0, s46
	s_nop 0
	global_load_lds_dwordx4 v[152:153], off
	s_waitcnt vmcnt(8)
	s_waitcnt lgkmcnt(0)
	s_barrier
	s_setprio 1
	s_waitcnt lgkmcnt(0)
	v_mfma_f32_16x16x32_bf16 v[60:63], v[144:147], v[196:199], v[60:63]
	v_mfma_f32_16x16x32_bf16 v[56:59], v[170:173], v[196:199], v[56:59]
	v_mfma_f32_16x16x32_bf16 v[52:55], v[144:147], v[204:207], v[52:55]
	v_mfma_f32_16x16x32_bf16 v[48:51], v[170:173], v[204:207], v[48:51]
	v_mfma_f32_16x16x32_bf16 v[44:47], v[144:147], v[212:215], v[44:47]
	v_mfma_f32_16x16x32_bf16 v[40:43], v[170:173], v[212:215], v[40:43]
	v_mfma_f32_16x16x32_bf16 v[36:39], v[144:147], v[220:223], v[36:39]
	v_mfma_f32_16x16x32_bf16 v[32:35], v[170:173], v[220:223], v[32:35]
	v_mfma_f32_16x16x32_bf16 v[60:63], v[148:151], v[200:203], v[60:63]
	v_mfma_f32_16x16x32_bf16 v[56:59], v[174:177], v[200:203], v[56:59]
	v_mfma_f32_16x16x32_bf16 v[52:55], v[148:151], v[208:211], v[52:55]
	v_mfma_f32_16x16x32_bf16 v[48:51], v[174:177], v[208:211], v[48:51]
	v_mfma_f32_16x16x32_bf16 v[44:47], v[148:151], v[216:219], v[44:47]
	v_mfma_f32_16x16x32_bf16 v[40:43], v[174:177], v[216:219], v[40:43]
	v_mfma_f32_16x16x32_bf16 v[36:39], v[148:151], v[224:227], v[36:39]
	v_mfma_f32_16x16x32_bf16 v[32:35], v[174:177], v[224:227], v[32:35]
	s_setprio 0
	s_setprio 1
	v_mfma_f32_16x16x32_bf16 v[28:31], v[178:181], v[196:199], v[28:31]
	v_mfma_f32_16x16x32_bf16 v[24:27], v[188:191], v[196:199], v[24:27]
	v_mfma_f32_16x16x32_bf16 v[20:23], v[178:181], v[204:207], v[20:23]
	v_mfma_f32_16x16x32_bf16 v[16:19], v[188:191], v[204:207], v[16:19]
	v_mfma_f32_16x16x32_bf16 v[12:15], v[178:181], v[212:215], v[12:15]
	v_mfma_f32_16x16x32_bf16 v[8:11], v[188:191], v[212:215], v[8:11]
	v_mfma_f32_16x16x32_bf16 v[4:7], v[178:181], v[220:223], v[4:7]
	v_mfma_f32_16x16x32_bf16 v[0:3], v[188:191], v[220:223], v[0:3]
	v_mfma_f32_16x16x32_bf16 v[28:31], v[184:187], v[200:203], v[28:31]
	v_mfma_f32_16x16x32_bf16 v[24:27], v[192:195], v[200:203], v[24:27]
	v_mfma_f32_16x16x32_bf16 v[20:23], v[184:187], v[208:211], v[20:23]
	v_mfma_f32_16x16x32_bf16 v[16:19], v[192:195], v[208:211], v[16:19]
	v_mfma_f32_16x16x32_bf16 v[12:15], v[184:187], v[216:219], v[12:15]
	v_mfma_f32_16x16x32_bf16 v[8:11], v[192:195], v[216:219], v[8:11]
	v_mfma_f32_16x16x32_bf16 v[4:7], v[184:187], v[224:227], v[4:7]
	v_mfma_f32_16x16x32_bf16 v[0:3], v[192:195], v[224:227], v[0:3]
	s_barrier
	s_setprio 0
	s_add_i32 s57, s57, 2
	s_add_u32 s30, s30, 0x100
	s_addc_u32 s31, s31, 0
	s_add_u32 s55, s55, 0x100
	s_addc_u32 s56, s56, 0
	s_cmp_gt_u32 s57, 29
	s_cbranch_scc0 .LBB0_953
	s_and_b64 vcc, exec, s[16:17]
	s_cbranch_vccz .LBB0_956
	s_barrier

; #define PG8_STAGE(bufoff, gbase, voff) do { _Pragma("unroll") for (int _i = 0; _i < 2; ++_i) \
;         __builtin_amdgcn_global_load_lds((const unsigned*)((const char*)(gbase) + (voff)[_i]), (PG8_LAS unsigned*)(lds + (bufoff) + ldsw + _i * 8192), 16, 0, 0); } while (0)
; #define PG8_LDA(dst, b, h) do { _Pragma("unroll") for (int m = 0; m < 4; ++m) _Pragma("unroll") for (int k = 0; k < 2; ++k) dst[m][k] = *(const PG8_LAS bf16x8*)(lds + PG8_SA(b, h) + aoff + m * 2048 + k * 1024); } while (0)
; #define PG8_LDB(dst, b, h) do { _Pragma("unroll") for (int n = 0; n < 2; ++n) _Pragma("unroll") for (int k = 0; k < 2; ++k) dst[n][k] = *(const PG8_LAS bf16x8*)(lds + PG8_SB(b, h) + boff + n * 2048 + k * 1024); } while (0)
; #define PG8_MMA(ai, bj, At, Bt) do { __builtin_amdgcn_s_setprio(1); _Pragma("unroll") for (int m = 0; m < 4; ++m) _Pragma("unroll") for (int n = 0; n < 2; ++n) _Pragma("unroll") for (int k = 0; k < 2; ++k) \
;         acc[ai][bj][m][n] = __builtin_amdgcn_mfma_f32_16x16x32_bf16(Bt[n][k], At[m][k], acc[ai][bj][m][n], 0, 0, 0); __builtin_amdgcn_s_setprio(0); } while (0)
; #define PG8_WAIT_V(n) asm volatile("s_waitcnt vmcnt(" #n ")" ::: "memory")
; #define PG8_WAIT_L(n) asm volatile("s_waitcnt lgkmcnt(" #n ")" ::: "memory")
; #define PG8_BAR __builtin_amdgcn_s_barrier()
; #define PG8_SCHED __builtin_amdgcn_sched_barrier(0)
; template <class Epi, class Sched, bool ALIGN_EPI = false, bool SP2 = false>
; __device__ __forceinline__ void gemm_phase(PG8_LAS unsigned char* lds, const Gemm g, const Sched& S, const Epi& E) {
;     ...
;             const char* a2 = last ? nA : cA + (size_t)(t + 2) * kstep; const char* b2 = last ? nB : cB + (size_t)(t + 2) * kstep;
;             const char* a3 = a2 + kstep; const char* b3 = b2 + kstep;
;             if (last && has_next) S.a_ready(nxt);
;             if constexpr (SP2) {
;             PG8_LDB(B0, 0, 0); PG8_LDB(B1, 0, 1); PG8_SCHED; PG8_LDA(At, 0, 0); PG8_STAGE(PG8_SA(1, 1), a1 + hstep, voffA);
;             PG8_WAIT_V(8); PG8_WAIT_L(0); PG8_BAR; PG8_MMA(0, 0, At, B0); PG8_MMA(0, 1, At, B1); PG8_BAR; PG8_SCHED;
;             PG8_LDA(At, 0, 1); PG8_STAGE(PG8_SB(0, 0), b2, voffB); PG8_STAGE(PG8_SB(0, 1), b2 + hstep, voffB); PG8_STAGE(PG8_SA(0, 0), a2, voffA);
;             PG8_WAIT_V(8); PG8_WAIT_L(0); PG8_BAR; PG8_MMA(1, 0, At, B0); PG8_MMA(1, 1, At, B1); PG8_BAR; PG8_SCHED;
.LBB0_1071:
	ds_read_b128 v[148:151], v162
	ds_read_b128 v[170:173], v162 offset:1024
	ds_read_b128 v[174:177], v162 offset:2048
	ds_read_b128 v[178:181], v162 offset:3072
	ds_read_b128 v[184:187], v163
	ds_read_b128 v[188:191], v163 offset:1024
	ds_read_b128 v[192:195], v163 offset:2048
	ds_read_b128 v[196:199], v163 offset:3072
	s_add_u32 s34, s30, 0xfff80080
	s_addc_u32 s35, s31, -1
	s_cmp_eq_u32 s58, 28
	s_cselect_b32 s37, s21, s35
	s_cselect_b32 s36, s29, s34
	s_cselect_b32 s35, s19, s57
	s_cselect_b32 s34, s55, s56
	v_lshl_add_u64 v[152:153], s[30:31], 0, v[140:141]
	s_add_i32 m0, s27, 0xc000
	ds_read_b128 v[200:203], v164
	ds_read_b128 v[204:207], v164 offset:1024
	ds_read_b128 v[208:211], v164 offset:2048
	ds_read_b128 v[212:215], v164 offset:3072
	ds_read_b128 v[216:219], v164 offset:4096
	ds_read_b128 v[220:223], v164 offset:5120
	ds_read_b128 v[224:227], v164 offset:6144
	ds_read_b128 v[228:231], v164 offset:7168
	global_load_lds_dwordx4 v[152:153], off
	v_lshl_add_u64 v[152:153], s[30:31], 0, v[142:143]
	s_add_i32 m0, s27, 0xe000
	s_nop 0
	global_load_lds_dwordx4 v[152:153], off
	s_waitcnt vmcnt(8)
	s_waitcnt lgkmcnt(0)
	s_barrier
	s_setprio 1
	s_waitcnt lgkmcnt(0)
	v_mfma_f32_16x16x32_bf16 v[124:127], v[148:151], v[200:203], v[124:127]
	v_mfma_f32_16x16x32_bf16 v[120:123], v[174:177], v[200:203], v[120:123]
	v_mfma_f32_16x16x32_bf16 v[116:119], v[148:151], v[208:211], v[116:119]
	v_mfma_f32_16x16x32_bf16 v[112:115], v[174:177], v[208:211], v[112:115]
	v_mfma_f32_16x16x32_bf16 v[108:111], v[148:151], v[216:219], v[108:111]
	v_mfma_f32_16x16x32_bf16 v[104:107], v[174:177], v[216:219], v[104:107]
	v_mfma_f32_16x16x32_bf16 v[100:103], v[148:151], v[224:227], v[100:103]
	v_mfma_f32_16x16x32_bf16 v[96:99], v[174:177], v[224:227], v[96:99]
	v_mfma_f32_16x16x32_bf16 v[124:127], v[170:173], v[204:207], v[124:127]
	v_mfma_f32_16x16x32_bf16 v[120:123], v[178:181], v[204:207], v[120:123]
	v_mfma_f32_16x16x32_bf16 v[116:119], v[170:173], v[212:215], v[116:119]
	v_mfma_f32_16x16x32_bf16 v[112:115], v[178:181], v[212:215], v[112:115]
	v_mfma_f32_16x16x32_bf16 v[108:111], v[170:173], v[220:223], v[108:111]
	v_mfma_f32_16x16x32_bf16 v[104:107], v[178:181], v[220:223], v[104:107]
	v_mfma_f32_16x16x32_bf16 v[100:103], v[170:173], v[228:231], v[100:103]
	v_mfma_f32_16x16x32_bf16 v[96:99], v[178:181], v[228:231], v[96:99]
	s_setprio 0
	s_setprio 1
	v_mfma_f32_16x16x32_bf16 v[92:95], v[184:187], v[200:203], v[92:95]
	v_mfma_f32_16x16x32_bf16 v[88:91], v[192:195], v[200:203], v[88:91]
	v_mfma_f32_16x16x32_bf16 v[84:87], v[184:187], v[208:211], v[84:87]
	v_mfma_f32_16x16x32_bf16 v[80:83], v[192:195], v[208:211], v[80:83]
	v_mfma_f32_16x16x32_bf16 v[76:79], v[184:187], v[216:219], v[76:79]
	v_mfma_f32_16x16x32_bf16 v[72:75], v[192:195], v[216:219], v[72:75]
	v_mfma_f32_16x16x32_bf16 v[68:71], v[184:187], v[224:227], v[68:71]
	v_mfma_f32_16x16x32_bf16 v[64:67], v[192:195], v[224:227], v[64:67]
	v_mfma_f32_16x16x32_bf16 v[92:95], v[188:191], v[204:207], v[92:95]
	v_mfma_f32_16x16x32_bf16 v[88:91], v[196:199], v[204:207], v[88:91]
	v_mfma_f32_16x16x32_bf16 v[84:87], v[188:191], v[212:215], v[84:87]
	v_mfma_f32_16x16x32_bf16 v[80:83], v[196:199], v[212:215], v[80:83]
	v_mfma_f32_16x16x32_bf16 v[76:79], v[188:191], v[220:223], v[76:79]
	v_mfma_f32_16x16x32_bf16 v[72:75], v[196:199], v[220:223], v[72:75]
	v_mfma_f32_16x16x32_bf16 v[68:71], v[188:191], v[228:231], v[68:71]
	v_mfma_f32_16x16x32_bf16 v[64:67], v[196:199], v[228:231], v[64:67]
	s_barrier
	s_setprio 0
	s_add_i32 s59, s52, s33
	v_lshl_add_u64 v[152:153], s[34:35], 0, v[130:131]
	s_mov_b32 m0, s59
	ds_read_b128 v[200:203], v164 offset:16384
	ds_read_b128 v[204:207], v164 offset:17408
	ds_read_b128 v[208:211], v164 offset:18432
	ds_read_b128 v[212:215], v164 offset:19456
	ds_read_b128 v[216:219], v164 offset:20480
	ds_read_b128 v[220:223], v164 offset:21504
	ds_read_b128 v[224:227], v164 offset:22528
	ds_read_b128 v[228:231], v164 offset:23552
	global_load_lds_dwordx4 v[152:153], off
	s_add_i32 m0, s59, 0x2000
	s_add_u32 s60, s34, 0x80000
	v_lshl_add_u64 v[232:233], s[34:35], 0, v[134:135]
	s_addc_u32 s61, s35, 0
	s_add_i32 s59, s53, s33
	global_load_lds_dwordx4 v[232:233], off
	v_lshl_add_u64 v[234:235], s[60:61], 0, v[130:131]
	s_mov_b32 m0, s59
	v_lshl_add_u64 v[236:237], s[36:37], 0, v[132:133]
	global_load_lds_dwordx4 v[234:235], off
	v_lshl_add_u64 v[234:235], s[60:61], 0, v[134:135]
	s_add_i32 m0, s59, 0x2000
	s_nop 0
	global_load_lds_dwordx4 v[234:235], off
	v_lshl_add_u64 v[234:235], s[36:37], 0, v[128:129]
	s_mov_b32 m0, s27
	s_nop 0
	global_load_lds_dwordx4 v[234:235], off
	s_mov_b32 m0, s42
	s_nop 0
	global_load_lds_dwordx4 v[236:237], off
	s_waitcnt vmcnt(8)
	s_waitcnt lgkmcnt(0)
	s_barrier
; #define PG8_STAGE(bufoff, gbase, voff) do { _Pragma("unroll") for (int _i = 0; _i < 2; ++_i) \
;         __builtin_amdgcn_global_load_lds((const unsigned*)((const char*)(gbase) + (voff)[_i]), (PG8_LAS unsigned*)(lds + (bufoff) + ldsw + _i * 8192), 16, 0, 0); } while (0)
; #define PG8_LDA(dst, b, h) do { _Pragma("unroll") for (int m = 0; m < 4; ++m) _Pragma("unroll") for (int k = 0; k < 2; ++k) dst[m][k] = *(const PG8_LAS bf16x8*)(lds + PG8_SA(b, h) + aoff + m * 2048 + k * 1024); } while (0)
; #define PG8_LDB(dst, b, h) do { _Pragma("unroll") for (int n = 0; n < 2; ++n) _Pragma("unroll") for (int k = 0; k < 2; ++k) dst[n][k] = *(const PG8_LAS bf16x8*)(lds + PG8_SB(b, h) + boff + n * 2048 + k * 1024); } while (0)
; #define PG8_MMA(ai, bj, At, Bt) do { __builtin_amdgcn_s_setprio(1); _Pragma("unroll") for (int m = 0; m < 4; ++m) _Pragma("unroll") for (int n = 0; n < 2; ++n) _Pragma("unroll") for (int k = 0; k < 2; ++k) \
;         acc[ai][bj][m][n] = __builtin_amdgcn_mfma_f32_16x16x32_bf16(Bt[n][k], At[m][k], acc[ai][bj][m][n], 0, 0, 0); __builtin_amdgcn_s_setprio(0); } while (0)
; #define PG8_WAIT_V(n) asm volatile("s_waitcnt vmcnt(" #n ")" ::: "memory")
; #define PG8_WAIT_L(n) asm volatile("s_waitcnt lgkmcnt(" #n ")" ::: "memory")
; #define PG8_BAR __builtin_amdgcn_s_barrier()
; #define PG8_SCHED __builtin_amdgcn_sched_barrier(0)
; template <class Epi, class Sched, bool ALIGN_EPI = false, bool SP2 = false>
; __device__ __forceinline__ void gemm_phase(PG8_LAS unsigned char* lds, const Gemm g, const Sched& S, const Epi& E) {
;     ...
;             PG8_WAIT_V(8); PG8_WAIT_L(0); PG8_BAR; PG8_MMA(1, 0, At, B0); PG8_MMA(1, 1, At, B1); PG8_BAR; PG8_SCHED;
;             PG8_LDB(B0, 1, 0); PG8_LDB(B1, 1, 1); PG8_SCHED; PG8_LDA(At, 1, 0); PG8_STAGE(PG8_SA(0, 1), a2 + hstep, voffA);
;             PG8_WAIT_V(8); PG8_WAIT_L(0); PG8_BAR; PG8_MMA(0, 0, At, B0); PG8_MMA(0, 1, At, B1); PG8_BAR; PG8_SCHED;
	s_setprio 1
	s_waitcnt lgkmcnt(0)
	v_mfma_f32_16x16x32_bf16 v[60:63], v[148:151], v[200:203], v[60:63]
	v_mfma_f32_16x16x32_bf16 v[56:59], v[174:177], v[200:203], v[56:59]
	v_mfma_f32_16x16x32_bf16 v[52:55], v[148:151], v[208:211], v[52:55]
	v_mfma_f32_16x16x32_bf16 v[48:51], v[174:177], v[208:211], v[48:51]
	v_mfma_f32_16x16x32_bf16 v[44:47], v[148:151], v[216:219], v[44:47]
	v_mfma_f32_16x16x32_bf16 v[40:43], v[174:177], v[216:219], v[40:43]
	v_mfma_f32_16x16x32_bf16 v[36:39], v[148:151], v[224:227], v[36:39]
	v_mfma_f32_16x16x32_bf16 v[32:35], v[174:177], v[224:227], v[32:35]
	v_mfma_f32_16x16x32_bf16 v[60:63], v[170:173], v[204:207], v[60:63]
	v_mfma_f32_16x16x32_bf16 v[56:59], v[178:181], v[204:207], v[56:59]
	v_mfma_f32_16x16x32_bf16 v[52:55], v[170:173], v[212:215], v[52:55]
	v_mfma_f32_16x16x32_bf16 v[48:51], v[178:181], v[212:215], v[48:51]
	v_mfma_f32_16x16x32_bf16 v[44:47], v[170:173], v[220:223], v[44:47]
	v_mfma_f32_16x16x32_bf16 v[40:43], v[178:181], v[220:223], v[40:43]
	v_mfma_f32_16x16x32_bf16 v[36:39], v[170:173], v[228:231], v[36:39]
	v_mfma_f32_16x16x32_bf16 v[32:35], v[178:181], v[228:231], v[32:35]
	s_setprio 0
	s_setprio 1
	v_mfma_f32_16x16x32_bf16 v[28:31], v[184:187], v[200:203], v[28:31]
	v_mfma_f32_16x16x32_bf16 v[24:27], v[192:195], v[200:203], v[24:27]
	v_mfma_f32_16x16x32_bf16 v[20:23], v[184:187], v[208:211], v[20:23]
	v_mfma_f32_16x16x32_bf16 v[16:19], v[192:195], v[208:211], v[16:19]
	v_mfma_f32_16x16x32_bf16 v[12:15], v[184:187], v[216:219], v[12:15]
	v_mfma_f32_16x16x32_bf16 v[8:11], v[192:195], v[216:219], v[8:11]
	v_mfma_f32_16x16x32_bf16 v[4:7], v[184:187], v[224:227], v[4:7]
	v_mfma_f32_16x16x32_bf16 v[0:3], v[192:195], v[224:227], v[0:3]
	v_mfma_f32_16x16x32_bf16 v[28:31], v[188:191], v[204:207], v[28:31]
	v_mfma_f32_16x16x32_bf16 v[24:27], v[196:199], v[204:207], v[24:27]
	v_mfma_f32_16x16x32_bf16 v[20:23], v[188:191], v[212:215], v[20:23]
	v_mfma_f32_16x16x32_bf16 v[16:19], v[196:199], v[212:215], v[16:19]
	v_mfma_f32_16x16x32_bf16 v[12:15], v[188:191], v[220:223], v[12:15]
	v_mfma_f32_16x16x32_bf16 v[8:11], v[196:199], v[220:223], v[8:11]
	v_mfma_f32_16x16x32_bf16 v[4:7], v[188:191], v[228:231], v[4:7]
	v_mfma_f32_16x16x32_bf16 v[0:3], v[196:199], v[228:231], v[0:3]
	s_barrier
	s_setprio 0
	s_add_i32 s59, 0, 0x18000
	v_add_u32_e32 v136, s59, v160
	s_add_i32 s60, 0, 0x1c000
	ds_read_b128 v[148:151], v136
	ds_read_b128 v[170:173], v136 offset:1024
	ds_read_b128 v[174:177], v136 offset:2048
	ds_read_b128 v[178:181], v136 offset:3072
	v_add_u32_e32 v136, s60, v160
	ds_read_b128 v[184:187], v136
	ds_read_b128 v[188:191], v136 offset:1024
	ds_read_b128 v[192:195], v136 offset:2048
	ds_read_b128 v[196:199], v136 offset:3072
	s_add_u32 s36, s36, 0x80000
	s_addc_u32 s37, s37, 0
	s_mov_b32 m0, s43
	v_lshl_add_u64 v[238:239], s[36:37], 0, v[128:129]
	ds_read_b128 v[200:203], v164 offset:32768
	ds_read_b128 v[204:207], v164 offset:33792
	ds_read_b128 v[208:211], v164 offset:34816
	ds_read_b128 v[212:215], v164 offset:35840
	ds_read_b128 v[216:219], v164 offset:36864
	ds_read_b128 v[220:223], v164 offset:37888
	ds_read_b128 v[224:227], v164 offset:38912
	ds_read_b128 v[228:231], v164 offset:39936
	global_load_lds_dwordx4 v[238:239], off
	v_lshl_add_u64 v[238:239], s[36:37], 0, v[132:133]
	s_mov_b32 m0, s44
	s_nop 0
	global_load_lds_dwordx4 v[238:239], off
	s_waitcnt vmcnt(8)
	s_waitcnt lgkmcnt(0)
	s_barrier
	s_setprio 1
	s_waitcnt lgkmcnt(0)
	v_mfma_f32_16x16x32_bf16 v[124:127], v[148:151], v[200:203], v[124:127]
	v_mfma_f32_16x16x32_bf16 v[120:123], v[174:177], v[200:203], v[120:123]
	v_mfma_f32_16x16x32_bf16 v[116:119], v[148:151], v[208:211], v[116:119]
	v_mfma_f32_16x16x32_bf16 v[112:115], v[174:177], v[208:211], v[112:115]
	v_mfma_f32_16x16x32_bf16 v[108:111], v[148:151], v[216:219], v[108:111]
	v_mfma_f32_16x16x32_bf16 v[104:107], v[174:177], v[216:219], v[104:107]
	v_mfma_f32_16x16x32_bf16 v[100:103], v[148:151], v[224:227], v[100:103]
	v_mfma_f32_16x16x32_bf16 v[96:99], v[174:177], v[224:227], v[96:99]
	v_mfma_f32_16x16x32_bf16 v[124:127], v[170:173], v[204:207], v[124:127]
	v_mfma_f32_16x16x32_bf16 v[120:123], v[178:181], v[204:207], v[120:123]
	v_mfma_f32_16x16x32_bf16 v[116:119], v[170:173], v[212:215], v[116:119]
	v_mfma_f32_16x16x32_bf16 v[112:115], v[178:181], v[212:215], v[112:115]
	v_mfma_f32_16x16x32_bf16 v[108:111], v[170:173], v[220:223], v[108:111]
	v_mfma_f32_16x16x32_bf16 v[104:107], v[178:181], v[220:223], v[104:107]
	v_mfma_f32_16x16x32_bf16 v[100:103], v[170:173], v[228:231], v[100:103]
	v_mfma_f32_16x16x32_bf16 v[96:99], v[178:181], v[228:231], v[96:99]
	s_setprio 0
	s_setprio 1
	v_mfma_f32_16x16x32_bf16 v[92:95], v[184:187], v[200:203], v[92:95]
	v_mfma_f32_16x16x32_bf16 v[88:91], v[192:195], v[200:203], v[88:91]
	v_mfma_f32_16x16x32_bf16 v[84:87], v[184:187], v[208:211], v[84:87]
	v_mfma_f32_16x16x32_bf16 v[80:83], v[192:195], v[208:211], v[80:83]
	v_mfma_f32_16x16x32_bf16 v[76:79], v[184:187], v[216:219], v[76:79]
	v_mfma_f32_16x16x32_bf16 v[72:75], v[192:195], v[216:219], v[72:75]
	v_mfma_f32_16x16x32_bf16 v[68:71], v[184:187], v[224:227], v[68:71]
	v_mfma_f32_16x16x32_bf16 v[64:67], v[192:195], v[224:227], v[64:67]
	v_mfma_f32_16x16x32_bf16 v[92:95], v[188:191], v[204:207], v[92:95]
	v_mfma_f32_16x16x32_bf16 v[88:91], v[196:199], v[204:207], v[88:91]
	v_mfma_f32_16x16x32_bf16 v[84:87], v[188:191], v[212:215], v[84:87]
	v_mfma_f32_16x16x32_bf16 v[80:83], v[196:199], v[212:215], v[80:83]
	v_mfma_f32_16x16x32_bf16 v[76:79], v[188:191], v[220:223], v[76:79]
	v_mfma_f32_16x16x32_bf16 v[72:75], v[196:199], v[220:223], v[72:75]
	v_mfma_f32_16x16x32_bf16 v[68:71], v[188:191], v[228:231], v[68:71]
	v_mfma_f32_16x16x32_bf16 v[64:67], v[196:199], v[228:231], v[64:67]
	s_barrier
; #define PG8_STAGE(bufoff, gbase, voff) do { _Pragma("unroll") for (int _i = 0; _i < 2; ++_i) \
;         __builtin_amdgcn_global_load_lds((const unsigned*)((const char*)(gbase) + (voff)[_i]), (PG8_LAS unsigned*)(lds + (bufoff) + ldsw + _i * 8192), 16, 0, 0); } while (0)
; #define PG8_LDA(dst, b, h) do { _Pragma("unroll") for (int m = 0; m < 4; ++m) _Pragma("unroll") for (int k = 0; k < 2; ++k) dst[m][k] = *(const PG8_LAS bf16x8*)(lds + PG8_SA(b, h) + aoff + m * 2048 + k * 1024); } while (0)
; #define PG8_MMA(ai, bj, At, Bt) do { __builtin_amdgcn_s_setprio(1); _Pragma("unroll") for (int m = 0; m < 4; ++m) _Pragma("unroll") for (int n = 0; n < 2; ++n) _Pragma("unroll") for (int k = 0; k < 2; ++k) \
;         acc[ai][bj][m][n] = __builtin_amdgcn_mfma_f32_16x16x32_bf16(Bt[n][k], At[m][k], acc[ai][bj][m][n], 0, 0, 0); __builtin_amdgcn_s_setprio(0); } while (0)
; #define PG8_WAIT_V(n) asm volatile("s_waitcnt vmcnt(" #n ")" ::: "memory")
; #define PG8_WAIT_L(n) asm volatile("s_waitcnt lgkmcnt(" #n ")" ::: "memory")
; #define PG8_BAR __builtin_amdgcn_s_barrier()
; #define PG8_SCHED __builtin_amdgcn_sched_barrier(0)
; template <class Epi, class Sched, bool ALIGN_EPI = false, bool SP2 = false>
; __device__ __forceinline__ void gemm_phase(PG8_LAS unsigned char* lds, const Gemm g, const Sched& S, const Epi& E) {
;     ...
;             PG8_LDA(At, 1, 1); PG8_STAGE(PG8_SB(1, 0), b3, voffB); PG8_STAGE(PG8_SB(1, 1), b3 + hstep, voffB); PG8_STAGE(PG8_SA(1, 0), a3, voffA);
;             PG8_WAIT_V(8); PG8_WAIT_L(0); PG8_BAR; PG8_MMA(1, 0, At, B0); PG8_MMA(1, 1, At, B1); PG8_BAR; PG8_SCHED;
	s_setprio 0
	s_add_i32 s36, s59, s33
	v_lshl_add_u64 v[152:153], v[152:153], 0, s[14:15]
	s_mov_b32 m0, s36
	ds_read_b128 v[200:203], v164 offset:49152
	ds_read_b128 v[204:207], v164 offset:50176
	ds_read_b128 v[208:211], v164 offset:51200
	ds_read_b128 v[212:215], v164 offset:52224
	ds_read_b128 v[216:219], v164 offset:53248
	ds_read_b128 v[220:223], v164 offset:54272
	ds_read_b128 v[224:227], v164 offset:55296
	ds_read_b128 v[228:231], v164 offset:56320
	global_load_lds_dwordx4 v[152:153], off
	s_add_i32 m0, s36, 0x2000
	s_add_u32 s34, s34, 0x80080
	v_lshl_add_u64 v[152:153], v[232:233], 0, s[14:15]
	s_addc_u32 s35, s35, 0
	s_add_i32 s36, s60, s33
	global_load_lds_dwordx4 v[152:153], off
	v_lshl_add_u64 v[152:153], s[34:35], 0, v[130:131]
	s_mov_b32 m0, s36
	s_nop 0
	global_load_lds_dwordx4 v[152:153], off
	v_lshl_add_u64 v[152:153], s[34:35], 0, v[134:135]
	s_add_i32 m0, s36, 0x2000
	s_nop 0
	global_load_lds_dwordx4 v[152:153], off
	v_lshl_add_u64 v[152:153], v[234:235], 0, s[14:15]
	s_mov_b32 m0, s46
	s_nop 0
	global_load_lds_dwordx4 v[152:153], off
	v_lshl_add_u64 v[152:153], v[236:237], 0, s[14:15]
	s_mov_b32 m0, s47
	s_nop 0
	global_load_lds_dwordx4 v[152:153], off
	s_waitcnt vmcnt(8)
	s_waitcnt lgkmcnt(0)
	s_barrier
	s_setprio 1
	s_waitcnt lgkmcnt(0)
	v_mfma_f32_16x16x32_bf16 v[60:63], v[148:151], v[200:203], v[60:63]
	v_mfma_f32_16x16x32_bf16 v[56:59], v[174:177], v[200:203], v[56:59]
	v_mfma_f32_16x16x32_bf16 v[52:55], v[148:151], v[208:211], v[52:55]
	v_mfma_f32_16x16x32_bf16 v[48:51], v[174:177], v[208:211], v[48:51]
	v_mfma_f32_16x16x32_bf16 v[44:47], v[148:151], v[216:219], v[44:47]
	v_mfma_f32_16x16x32_bf16 v[40:43], v[174:177], v[216:219], v[40:43]
	v_mfma_f32_16x16x32_bf16 v[36:39], v[148:151], v[224:227], v[36:39]
	v_mfma_f32_16x16x32_bf16 v[32:35], v[174:177], v[224:227], v[32:35]
	v_mfma_f32_16x16x32_bf16 v[60:63], v[170:173], v[204:207], v[60:63]
	v_mfma_f32_16x16x32_bf16 v[56:59], v[178:181], v[204:207], v[56:59]
	v_mfma_f32_16x16x32_bf16 v[52:55], v[170:173], v[212:215], v[52:55]
	v_mfma_f32_16x16x32_bf16 v[48:51], v[178:181], v[212:215], v[48:51]
	v_mfma_f32_16x16x32_bf16 v[44:47], v[170:173], v[220:223], v[44:47]
	v_mfma_f32_16x16x32_bf16 v[40:43], v[178:181], v[220:223], v[40:43]
	v_mfma_f32_16x16x32_bf16 v[36:39], v[170:173], v[228:231], v[36:39]
	v_mfma_f32_16x16x32_bf16 v[32:35], v[178:181], v[228:231], v[32:35]
	s_setprio 0
	s_setprio 1
	v_mfma_f32_16x16x32_bf16 v[28:31], v[184:187], v[200:203], v[28:31]
	v_mfma_f32_16x16x32_bf16 v[24:27], v[192:195], v[200:203], v[24:27]
	v_mfma_f32_16x16x32_bf16 v[20:23], v[184:187], v[208:211], v[20:23]
	v_mfma_f32_16x16x32_bf16 v[16:19], v[192:195], v[208:211], v[16:19]
	v_mfma_f32_16x16x32_bf16 v[12:15], v[184:187], v[216:219], v[12:15]
	v_mfma_f32_16x16x32_bf16 v[8:11], v[192:195], v[216:219], v[8:11]
	v_mfma_f32_16x16x32_bf16 v[4:7], v[184:187], v[224:227], v[4:7]
	v_mfma_f32_16x16x32_bf16 v[0:3], v[192:195], v[224:227], v[0:3]
	v_mfma_f32_16x16x32_bf16 v[28:31], v[188:191], v[204:207], v[28:31]
	v_mfma_f32_16x16x32_bf16 v[24:27], v[196:199], v[204:207], v[24:27]
	v_mfma_f32_16x16x32_bf16 v[20:23], v[188:191], v[212:215], v[20:23]
	v_mfma_f32_16x16x32_bf16 v[16:19], v[196:199], v[212:215], v[16:19]
	v_mfma_f32_16x16x32_bf16 v[12:15], v[188:191], v[220:223], v[12:15]
	v_mfma_f32_16x16x32_bf16 v[8:11], v[196:199], v[220:223], v[8:11]
	v_mfma_f32_16x16x32_bf16 v[4:7], v[188:191], v[228:231], v[4:7]
	v_mfma_f32_16x16x32_bf16 v[0:3], v[196:199], v[228:231], v[0:3]
	s_barrier
	s_setprio 0
	s_add_i32 s58, s58, 2
	s_add_u32 s30, s30, 0x100
	s_addc_u32 s31, s31, 0
	s_add_u32 s56, s56, 0x100
	s_addc_u32 s57, s57, 0
	s_cmp_gt_u32 s58, 29
	s_cbranch_scc0 .LBB0_1071
	s_and_b64 vcc, exec, s[16:17]
	s_cbranch_vccz .LBB0_1074
	s_barrier

; #define PG8_STAGE(bufoff, gbase, voff) do { _Pragma("unroll") for (int _i = 0; _i < 2; ++_i) \
;         __builtin_amdgcn_global_load_lds((const unsigned*)((const char*)(gbase) + (voff)[_i]), (PG8_LAS unsigned*)(lds + (bufoff) + ldsw + _i * 8192), 16, 0, 0); } while (0)
; #define PG8_LDA(dst, b, h) do { _Pragma("unroll") for (int m = 0; m < 4; ++m) _Pragma("unroll") for (int k = 0; k < 2; ++k) dst[m][k] = *(const PG8_LAS bf16x8*)(lds + PG8_SA(b, h) + aoff + m * 2048 + k * 1024); } while (0)
; #define PG8_LDB(dst, b, h) do { _Pragma("unroll") for (int n = 0; n < 2; ++n) _Pragma("unroll") for (int k = 0; k < 2; ++k) dst[n][k] = *(const PG8_LAS bf16x8*)(lds + PG8_SB(b, h) + boff + n * 2048 + k * 1024); } while (0)
; #define PG8_MMA(ai, bj, At, Bt) do { __builtin_amdgcn_s_setprio(1); _Pragma("unroll") for (int m = 0; m < 4; ++m) _Pragma("unroll") for (int n = 0; n < 2; ++n) _Pragma("unroll") for (int k = 0; k < 2; ++k) \
;         acc[ai][bj][m][n] = __builtin_amdgcn_mfma_f32_16x16x32_bf16(Bt[n][k], At[m][k], acc[ai][bj][m][n], 0, 0, 0); __builtin_amdgcn_s_setprio(0); } while (0)
; #define PG8_WAIT_V(n) asm volatile("s_waitcnt vmcnt(" #n ")" ::: "memory")
; #define PG8_WAIT_L(n) asm volatile("s_waitcnt lgkmcnt(" #n ")" ::: "memory")
; #define PG8_BAR __builtin_amdgcn_s_barrier()
; #define PG8_SCHED __builtin_amdgcn_sched_barrier(0)
; template <class Epi, class Sched, bool ALIGN_EPI = false, bool SP2 = false>
; __device__ __forceinline__ void gemm_phase(PG8_LAS unsigned char* lds, const Gemm g, const Sched& S, const Epi& E) {
;     ...
;             const char* a2 = last ? nA : cA + (size_t)(t + 2) * kstep; const char* b2 = last ? nB : cB + (size_t)(t + 2) * kstep;
;             const char* a3 = a2 + kstep; const char* b3 = b2 + kstep;
;             if (last && has_next) S.a_ready(nxt);
;             if constexpr (SP2) {
;             PG8_LDB(B0, 0, 0); PG8_LDB(B1, 0, 1); PG8_SCHED; PG8_LDA(At, 0, 0); PG8_STAGE(PG8_SA(1, 1), a1 + hstep, voffA);
;             PG8_WAIT_V(8); PG8_WAIT_L(0); PG8_BAR; PG8_MMA(0, 0, At, B0); PG8_MMA(0, 1, At, B1); PG8_BAR; PG8_SCHED;
;             PG8_LDA(At, 0, 1); PG8_STAGE(PG8_SB(0, 0), b2, voffB); PG8_STAGE(PG8_SB(0, 1), b2 + hstep, voffB); PG8_STAGE(PG8_SA(0, 0), a2, voffA);
;             PG8_WAIT_V(8); PG8_WAIT_L(0); PG8_BAR; PG8_MMA(1, 0, At, B0); PG8_MMA(1, 1, At, B1); PG8_BAR; PG8_SCHED;
.LBB0_1343:
	v_add_u32_e32 v134, s46, v161
	ds_read_b128 v[144:147], v134
	ds_read_b128 v[166:169], v134 offset:1024
	ds_read_b128 v[170:173], v134 offset:2048
	ds_read_b128 v[174:177], v134 offset:3072
	v_add_u32_e32 v134, s47, v161
	ds_read_b128 v[178:181], v134
	ds_read_b128 v[184:187], v134 offset:1024
	ds_read_b128 v[188:191], v134 offset:2048
	ds_read_b128 v[192:195], v134 offset:3072
	s_add_u32 s34, s30, 0xfff00080
	s_addc_u32 s35, s31, -1
	s_cmp_eq_u32 s56, 60
	s_cselect_b32 s37, s21, s35
	s_cselect_b32 s36, s27, s34
	s_cselect_b32 s35, s19, s55
	s_cselect_b32 s34, s49, s54
	v_lshl_add_u64 v[148:149], s[30:31], 0, v[136:137]
	s_add_i32 m0, s29, 0xc000
	ds_read_b128 v[196:199], v163
	ds_read_b128 v[200:203], v163 offset:1024
	ds_read_b128 v[204:207], v163 offset:2048
	ds_read_b128 v[208:211], v163 offset:3072
	ds_read_b128 v[212:215], v163 offset:4096
	ds_read_b128 v[216:219], v163 offset:5120
	ds_read_b128 v[220:223], v163 offset:6144
	ds_read_b128 v[224:227], v163 offset:7168
	global_load_lds_dwordx4 v[148:149], off
	v_lshl_add_u64 v[148:149], s[30:31], 0, v[138:139]
	s_add_i32 m0, s29, 0xe000
	s_nop 0
	global_load_lds_dwordx4 v[148:149], off
	s_waitcnt vmcnt(8)
	s_waitcnt lgkmcnt(0)
	s_barrier
	s_setprio 1
	s_waitcnt lgkmcnt(0)
	v_mfma_f32_16x16x32_bf16 v[120:123], v[144:147], v[196:199], v[120:123]
	v_mfma_f32_16x16x32_bf16 v[124:127], v[170:173], v[196:199], v[124:127]
	v_mfma_f32_16x16x32_bf16 v[112:115], v[144:147], v[204:207], v[112:115]
	v_mfma_f32_16x16x32_bf16 v[116:119], v[170:173], v[204:207], v[116:119]
	v_mfma_f32_16x16x32_bf16 v[104:107], v[144:147], v[212:215], v[104:107]
	v_mfma_f32_16x16x32_bf16 v[108:111], v[170:173], v[212:215], v[108:111]
	v_mfma_f32_16x16x32_bf16 v[96:99], v[144:147], v[220:223], v[96:99]
	v_mfma_f32_16x16x32_bf16 v[100:103], v[170:173], v[220:223], v[100:103]
	v_mfma_f32_16x16x32_bf16 v[120:123], v[166:169], v[200:203], v[120:123]
	v_mfma_f32_16x16x32_bf16 v[124:127], v[174:177], v[200:203], v[124:127]
	v_mfma_f32_16x16x32_bf16 v[112:115], v[166:169], v[208:211], v[112:115]
	v_mfma_f32_16x16x32_bf16 v[116:119], v[174:177], v[208:211], v[116:119]
	v_mfma_f32_16x16x32_bf16 v[104:107], v[166:169], v[216:219], v[104:107]
	v_mfma_f32_16x16x32_bf16 v[108:111], v[174:177], v[216:219], v[108:111]
	v_mfma_f32_16x16x32_bf16 v[96:99], v[166:169], v[224:227], v[96:99]
	v_mfma_f32_16x16x32_bf16 v[100:103], v[174:177], v[224:227], v[100:103]
	s_setprio 0
	s_setprio 1
	v_mfma_f32_16x16x32_bf16 v[76:79], v[178:181], v[196:199], v[76:79]
	v_mfma_f32_16x16x32_bf16 v[92:95], v[188:191], v[196:199], v[92:95]
	v_mfma_f32_16x16x32_bf16 v[72:75], v[178:181], v[204:207], v[72:75]
	v_mfma_f32_16x16x32_bf16 v[88:91], v[188:191], v[204:207], v[88:91]
	v_mfma_f32_16x16x32_bf16 v[68:71], v[178:181], v[212:215], v[68:71]
	v_mfma_f32_16x16x32_bf16 v[84:87], v[188:191], v[212:215], v[84:87]
	v_mfma_f32_16x16x32_bf16 v[64:67], v[178:181], v[220:223], v[64:67]
	v_mfma_f32_16x16x32_bf16 v[80:83], v[188:191], v[220:223], v[80:83]
	v_mfma_f32_16x16x32_bf16 v[76:79], v[184:187], v[200:203], v[76:79]
	v_mfma_f32_16x16x32_bf16 v[92:95], v[192:195], v[200:203], v[92:95]
	v_mfma_f32_16x16x32_bf16 v[72:75], v[184:187], v[208:211], v[72:75]
	v_mfma_f32_16x16x32_bf16 v[88:91], v[192:195], v[208:211], v[88:91]
	v_mfma_f32_16x16x32_bf16 v[68:71], v[184:187], v[216:219], v[68:71]
	v_mfma_f32_16x16x32_bf16 v[84:87], v[192:195], v[216:219], v[84:87]
	v_mfma_f32_16x16x32_bf16 v[64:67], v[184:187], v[224:227], v[64:67]
	v_mfma_f32_16x16x32_bf16 v[80:83], v[192:195], v[224:227], v[80:83]
	s_barrier
	s_setprio 0
	s_add_i32 s57, s46, s33
	v_lshl_add_u64 v[148:149], s[34:35], 0, v[128:129]
	s_mov_b32 m0, s57
	ds_read_b128 v[196:199], v163 offset:16384
	ds_read_b128 v[200:203], v163 offset:17408
	ds_read_b128 v[204:207], v163 offset:18432
	ds_read_b128 v[208:211], v163 offset:19456
	ds_read_b128 v[212:215], v163 offset:20480
	ds_read_b128 v[216:219], v163 offset:21504
	ds_read_b128 v[220:223], v163 offset:22528
	ds_read_b128 v[224:227], v163 offset:23552
	global_load_lds_dwordx4 v[148:149], off
	s_add_i32 m0, s57, 0x2000
	s_add_u32 s58, s34, 0x100000
	v_lshl_add_u64 v[228:229], s[34:35], 0, v[130:131]
	s_addc_u32 s59, s35, 0
	s_add_i32 s57, s47, s33
	global_load_lds_dwordx4 v[228:229], off
	v_lshl_add_u64 v[230:231], s[58:59], 0, v[128:129]
	s_mov_b32 m0, s57
	v_lshl_add_u64 v[232:233], s[36:37], 0, v[130:131]
	global_load_lds_dwordx4 v[230:231], off
	v_lshl_add_u64 v[230:231], s[58:59], 0, v[130:131]
	s_add_i32 m0, s57, 0x2000
	s_nop 0
	global_load_lds_dwordx4 v[230:231], off
	v_lshl_add_u64 v[230:231], s[36:37], 0, v[128:129]
	s_mov_b32 m0, s29
	s_nop 0
	global_load_lds_dwordx4 v[230:231], off
	s_mov_b32 m0, s38
	s_nop 0
	global_load_lds_dwordx4 v[232:233], off
	s_waitcnt vmcnt(8)
	s_waitcnt lgkmcnt(0)
	s_barrier
; #define PG8_STAGE(bufoff, gbase, voff) do { _Pragma("unroll") for (int _i = 0; _i < 2; ++_i) \
;         __builtin_amdgcn_global_load_lds((const unsigned*)((const char*)(gbase) + (voff)[_i]), (PG8_LAS unsigned*)(lds + (bufoff) + ldsw + _i * 8192), 16, 0, 0); } while (0)
; #define PG8_LDA(dst, b, h) do { _Pragma("unroll") for (int m = 0; m < 4; ++m) _Pragma("unroll") for (int k = 0; k < 2; ++k) dst[m][k] = *(const PG8_LAS bf16x8*)(lds + PG8_SA(b, h) + aoff + m * 2048 + k * 1024); } while (0)
; #define PG8_LDB(dst, b, h) do { _Pragma("unroll") for (int n = 0; n < 2; ++n) _Pragma("unroll") for (int k = 0; k < 2; ++k) dst[n][k] = *(const PG8_LAS bf16x8*)(lds + PG8_SB(b, h) + boff + n * 2048 + k * 1024); } while (0)
; #define PG8_MMA(ai, bj, At, Bt) do { __builtin_amdgcn_s_setprio(1); _Pragma("unroll") for (int m = 0; m < 4; ++m) _Pragma("unroll") for (int n = 0; n < 2; ++n) _Pragma("unroll") for (int k = 0; k < 2; ++k) \
;         acc[ai][bj][m][n] = __builtin_amdgcn_mfma_f32_16x16x32_bf16(Bt[n][k], At[m][k], acc[ai][bj][m][n], 0, 0, 0); __builtin_amdgcn_s_setprio(0); } while (0)
; #define PG8_WAIT_V(n) asm volatile("s_waitcnt vmcnt(" #n ")" ::: "memory")
; #define PG8_WAIT_L(n) asm volatile("s_waitcnt lgkmcnt(" #n ")" ::: "memory")
; #define PG8_BAR __builtin_amdgcn_s_barrier()
; #define PG8_SCHED __builtin_amdgcn_sched_barrier(0)
; template <class Epi, class Sched, bool ALIGN_EPI = false, bool SP2 = false>
; __device__ __forceinline__ void gemm_phase(PG8_LAS unsigned char* lds, const Gemm g, const Sched& S, const Epi& E) {
;     ...
;             PG8_WAIT_V(8); PG8_WAIT_L(0); PG8_BAR; PG8_MMA(1, 0, At, B0); PG8_MMA(1, 1, At, B1); PG8_BAR; PG8_SCHED;
;             PG8_LDB(B0, 1, 0); PG8_LDB(B1, 1, 1); PG8_SCHED; PG8_LDA(At, 1, 0); PG8_STAGE(PG8_SA(0, 1), a2 + hstep, voffA);
;             PG8_WAIT_V(8); PG8_WAIT_L(0); PG8_BAR; PG8_MMA(0, 0, At, B0); PG8_MMA(0, 1, At, B1); PG8_BAR; PG8_SCHED;
	s_setprio 1
	s_waitcnt lgkmcnt(0)
	v_mfma_f32_16x16x32_bf16 v[56:59], v[144:147], v[196:199], v[56:59]
	v_mfma_f32_16x16x32_bf16 v[60:63], v[170:173], v[196:199], v[60:63]
	v_mfma_f32_16x16x32_bf16 v[48:51], v[144:147], v[204:207], v[48:51]
	v_mfma_f32_16x16x32_bf16 v[52:55], v[170:173], v[204:207], v[52:55]
	v_mfma_f32_16x16x32_bf16 v[40:43], v[144:147], v[212:215], v[40:43]
	v_mfma_f32_16x16x32_bf16 v[44:47], v[170:173], v[212:215], v[44:47]
	v_mfma_f32_16x16x32_bf16 v[32:35], v[144:147], v[220:223], v[32:35]
	v_mfma_f32_16x16x32_bf16 v[36:39], v[170:173], v[220:223], v[36:39]
	v_mfma_f32_16x16x32_bf16 v[56:59], v[166:169], v[200:203], v[56:59]
	v_mfma_f32_16x16x32_bf16 v[60:63], v[174:177], v[200:203], v[60:63]
	v_mfma_f32_16x16x32_bf16 v[48:51], v[166:169], v[208:211], v[48:51]
	v_mfma_f32_16x16x32_bf16 v[52:55], v[174:177], v[208:211], v[52:55]
	v_mfma_f32_16x16x32_bf16 v[40:43], v[166:169], v[216:219], v[40:43]
	v_mfma_f32_16x16x32_bf16 v[44:47], v[174:177], v[216:219], v[44:47]
	v_mfma_f32_16x16x32_bf16 v[32:35], v[166:169], v[224:227], v[32:35]
	v_mfma_f32_16x16x32_bf16 v[36:39], v[174:177], v[224:227], v[36:39]
	s_setprio 0
	s_setprio 1
	v_mfma_f32_16x16x32_bf16 v[12:15], v[178:181], v[196:199], v[12:15]
	v_mfma_f32_16x16x32_bf16 v[28:31], v[188:191], v[196:199], v[28:31]
	v_mfma_f32_16x16x32_bf16 v[8:11], v[178:181], v[204:207], v[8:11]
	v_mfma_f32_16x16x32_bf16 v[24:27], v[188:191], v[204:207], v[24:27]
	v_mfma_f32_16x16x32_bf16 v[4:7], v[178:181], v[212:215], v[4:7]
	v_mfma_f32_16x16x32_bf16 v[20:23], v[188:191], v[212:215], v[20:23]
	v_mfma_f32_16x16x32_bf16 v[0:3], v[178:181], v[220:223], v[0:3]
	v_mfma_f32_16x16x32_bf16 v[16:19], v[188:191], v[220:223], v[16:19]
	v_mfma_f32_16x16x32_bf16 v[12:15], v[184:187], v[200:203], v[12:15]
	v_mfma_f32_16x16x32_bf16 v[28:31], v[192:195], v[200:203], v[28:31]
	v_mfma_f32_16x16x32_bf16 v[8:11], v[184:187], v[208:211], v[8:11]
	v_mfma_f32_16x16x32_bf16 v[24:27], v[192:195], v[208:211], v[24:27]
	v_mfma_f32_16x16x32_bf16 v[4:7], v[184:187], v[216:219], v[4:7]
	v_mfma_f32_16x16x32_bf16 v[20:23], v[192:195], v[216:219], v[20:23]
	v_mfma_f32_16x16x32_bf16 v[0:3], v[184:187], v[224:227], v[0:3]
	v_mfma_f32_16x16x32_bf16 v[16:19], v[192:195], v[224:227], v[16:19]
	s_barrier
	s_setprio 0
	s_add_i32 s57, 0, 0x18000
	v_add_u32_e32 v134, s57, v161
	s_add_i32 s58, 0, 0x1c000
	ds_read_b128 v[144:147], v134
	ds_read_b128 v[166:169], v134 offset:1024
	ds_read_b128 v[170:173], v134 offset:2048
	ds_read_b128 v[174:177], v134 offset:3072
	v_add_u32_e32 v134, s58, v161
	ds_read_b128 v[178:181], v134
	ds_read_b128 v[184:187], v134 offset:1024
	ds_read_b128 v[188:191], v134 offset:2048
	ds_read_b128 v[192:195], v134 offset:3072
	s_add_u32 s36, s36, 0x100000
	s_addc_u32 s37, s37, 0
	s_mov_b32 m0, s39
	v_lshl_add_u64 v[234:235], s[36:37], 0, v[128:129]
	ds_read_b128 v[196:199], v163 offset:32768
	ds_read_b128 v[200:203], v163 offset:33792
	ds_read_b128 v[204:207], v163 offset:34816
	ds_read_b128 v[208:211], v163 offset:35840
	ds_read_b128 v[212:215], v163 offset:36864
	ds_read_b128 v[216:219], v163 offset:37888
	ds_read_b128 v[220:223], v163 offset:38912
	ds_read_b128 v[224:227], v163 offset:39936
	global_load_lds_dwordx4 v[234:235], off
	v_lshl_add_u64 v[234:235], s[36:37], 0, v[130:131]
	s_mov_b32 m0, s40
	s_nop 0
	global_load_lds_dwordx4 v[234:235], off
	s_waitcnt vmcnt(8)
	s_waitcnt lgkmcnt(0)
	s_barrier
	s_setprio 1
	s_waitcnt lgkmcnt(0)
	v_mfma_f32_16x16x32_bf16 v[120:123], v[144:147], v[196:199], v[120:123]
	v_mfma_f32_16x16x32_bf16 v[124:127], v[170:173], v[196:199], v[124:127]
	v_mfma_f32_16x16x32_bf16 v[112:115], v[144:147], v[204:207], v[112:115]
	v_mfma_f32_16x16x32_bf16 v[116:119], v[170:173], v[204:207], v[116:119]
	v_mfma_f32_16x16x32_bf16 v[104:107], v[144:147], v[212:215], v[104:107]
	v_mfma_f32_16x16x32_bf16 v[108:111], v[170:173], v[212:215], v[108:111]
	v_mfma_f32_16x16x32_bf16 v[96:99], v[144:147], v[220:223], v[96:99]
	v_mfma_f32_16x16x32_bf16 v[100:103], v[170:173], v[220:223], v[100:103]
	v_mfma_f32_16x16x32_bf16 v[120:123], v[166:169], v[200:203], v[120:123]
	v_mfma_f32_16x16x32_bf16 v[124:127], v[174:177], v[200:203], v[124:127]
	v_mfma_f32_16x16x32_bf16 v[112:115], v[166:169], v[208:211], v[112:115]
	v_mfma_f32_16x16x32_bf16 v[116:119], v[174:177], v[208:211], v[116:119]
	v_mfma_f32_16x16x32_bf16 v[104:107], v[166:169], v[216:219], v[104:107]
	v_mfma_f32_16x16x32_bf16 v[108:111], v[174:177], v[216:219], v[108:111]
	v_mfma_f32_16x16x32_bf16 v[96:99], v[166:169], v[224:227], v[96:99]
	v_mfma_f32_16x16x32_bf16 v[100:103], v[174:177], v[224:227], v[100:103]
	s_setprio 0
	s_setprio 1
	v_mfma_f32_16x16x32_bf16 v[76:79], v[178:181], v[196:199], v[76:79]
	v_mfma_f32_16x16x32_bf16 v[92:95], v[188:191], v[196:199], v[92:95]
	v_mfma_f32_16x16x32_bf16 v[72:75], v[178:181], v[204:207], v[72:75]
	v_mfma_f32_16x16x32_bf16 v[88:91], v[188:191], v[204:207], v[88:91]
	v_mfma_f32_16x16x32_bf16 v[68:71], v[178:181], v[212:215], v[68:71]
	v_mfma_f32_16x16x32_bf16 v[84:87], v[188:191], v[212:215], v[84:87]
	v_mfma_f32_16x16x32_bf16 v[64:67], v[178:181], v[220:223], v[64:67]
	v_mfma_f32_16x16x32_bf16 v[80:83], v[188:191], v[220:223], v[80:83]
	v_mfma_f32_16x16x32_bf16 v[76:79], v[184:187], v[200:203], v[76:79]
	v_mfma_f32_16x16x32_bf16 v[92:95], v[192:195], v[200:203], v[92:95]
	v_mfma_f32_16x16x32_bf16 v[72:75], v[184:187], v[208:211], v[72:75]
	v_mfma_f32_16x16x32_bf16 v[88:91], v[192:195], v[208:211], v[88:91]
	v_mfma_f32_16x16x32_bf16 v[68:71], v[184:187], v[216:219], v[68:71]
	v_mfma_f32_16x16x32_bf16 v[84:87], v[192:195], v[216:219], v[84:87]
	v_mfma_f32_16x16x32_bf16 v[64:67], v[184:187], v[224:227], v[64:67]
	v_mfma_f32_16x16x32_bf16 v[80:83], v[192:195], v[224:227], v[80:83]
	s_barrier
; #define PG8_STAGE(bufoff, gbase, voff) do { _Pragma("unroll") for (int _i = 0; _i < 2; ++_i) \
;         __builtin_amdgcn_global_load_lds((const unsigned*)((const char*)(gbase) + (voff)[_i]), (PG8_LAS unsigned*)(lds + (bufoff) + ldsw + _i * 8192), 16, 0, 0); } while (0)
; #define PG8_LDA(dst, b, h) do { _Pragma("unroll") for (int m = 0; m < 4; ++m) _Pragma("unroll") for (int k = 0; k < 2; ++k) dst[m][k] = *(const PG8_LAS bf16x8*)(lds + PG8_SA(b, h) + aoff + m * 2048 + k * 1024); } while (0)
; #define PG8_MMA(ai, bj, At, Bt) do { __builtin_amdgcn_s_setprio(1); _Pragma("unroll") for (int m = 0; m < 4; ++m) _Pragma("unroll") for (int n = 0; n < 2; ++n) _Pragma("unroll") for (int k = 0; k < 2; ++k) \
;         acc[ai][bj][m][n] = __builtin_amdgcn_mfma_f32_16x16x32_bf16(Bt[n][k], At[m][k], acc[ai][bj][m][n], 0, 0, 0); __builtin_amdgcn_s_setprio(0); } while (0)
; #define PG8_WAIT_V(n) asm volatile("s_waitcnt vmcnt(" #n ")" ::: "memory")
; #define PG8_WAIT_L(n) asm volatile("s_waitcnt lgkmcnt(" #n ")" ::: "memory")
; #define PG8_BAR __builtin_amdgcn_s_barrier()
; #define PG8_SCHED __builtin_amdgcn_sched_barrier(0)
; template <class Epi, class Sched, bool ALIGN_EPI = false, bool SP2 = false>
; __device__ __forceinline__ void gemm_phase(PG8_LAS unsigned char* lds, const Gemm g, const Sched& S, const Epi& E) {
;     ...
;             PG8_LDA(At, 1, 1); PG8_STAGE(PG8_SB(1, 0), b3, voffB); PG8_STAGE(PG8_SB(1, 1), b3 + hstep, voffB); PG8_STAGE(PG8_SA(1, 0), a3, voffA);
;             PG8_WAIT_V(8); PG8_WAIT_L(0); PG8_BAR; PG8_MMA(1, 0, At, B0); PG8_MMA(1, 1, At, B1); PG8_BAR; PG8_SCHED;
	s_setprio 0
	s_add_i32 s36, s57, s33
	v_lshl_add_u64 v[148:149], v[148:149], 0, s[14:15]
	s_mov_b32 m0, s36
	ds_read_b128 v[196:199], v163 offset:49152
	ds_read_b128 v[200:203], v163 offset:50176
	ds_read_b128 v[204:207], v163 offset:51200
	ds_read_b128 v[208:211], v163 offset:52224
	ds_read_b128 v[212:215], v163 offset:53248
	ds_read_b128 v[216:219], v163 offset:54272
	ds_read_b128 v[220:223], v163 offset:55296
	ds_read_b128 v[224:227], v163 offset:56320
	global_load_lds_dwordx4 v[148:149], off
	s_add_i32 m0, s36, 0x2000
	s_add_u32 s34, s34, 0x100080
	v_lshl_add_u64 v[148:149], v[228:229], 0, s[14:15]
	s_addc_u32 s35, s35, 0
	s_add_i32 s36, s58, s33
	global_load_lds_dwordx4 v[148:149], off
	v_lshl_add_u64 v[148:149], s[34:35], 0, v[128:129]
	s_mov_b32 m0, s36
	s_nop 0
	global_load_lds_dwordx4 v[148:149], off
	v_lshl_add_u64 v[148:149], s[34:35], 0, v[130:131]
	s_add_i32 m0, s36, 0x2000
	s_nop 0
	global_load_lds_dwordx4 v[148:149], off
	v_lshl_add_u64 v[148:149], v[230:231], 0, s[14:15]
	s_mov_b32 m0, s41
	s_nop 0
	global_load_lds_dwordx4 v[148:149], off
	v_lshl_add_u64 v[148:149], v[232:233], 0, s[14:15]
	s_mov_b32 m0, s42
	s_nop 0
	global_load_lds_dwordx4 v[148:149], off
	s_waitcnt vmcnt(8)
	s_waitcnt lgkmcnt(0)
	s_barrier
	s_setprio 1
	s_waitcnt lgkmcnt(0)
	v_mfma_f32_16x16x32_bf16 v[56:59], v[144:147], v[196:199], v[56:59]
	v_mfma_f32_16x16x32_bf16 v[60:63], v[170:173], v[196:199], v[60:63]
	v_mfma_f32_16x16x32_bf16 v[48:51], v[144:147], v[204:207], v[48:51]
	v_mfma_f32_16x16x32_bf16 v[52:55], v[170:173], v[204:207], v[52:55]
	v_mfma_f32_16x16x32_bf16 v[40:43], v[144:147], v[212:215], v[40:43]
	v_mfma_f32_16x16x32_bf16 v[44:47], v[170:173], v[212:215], v[44:47]
	v_mfma_f32_16x16x32_bf16 v[32:35], v[144:147], v[220:223], v[32:35]
	v_mfma_f32_16x16x32_bf16 v[36:39], v[170:173], v[220:223], v[36:39]
	v_mfma_f32_16x16x32_bf16 v[56:59], v[166:169], v[200:203], v[56:59]
	v_mfma_f32_16x16x32_bf16 v[60:63], v[174:177], v[200:203], v[60:63]
	v_mfma_f32_16x16x32_bf16 v[48:51], v[166:169], v[208:211], v[48:51]
	v_mfma_f32_16x16x32_bf16 v[52:55], v[174:177], v[208:211], v[52:55]
	v_mfma_f32_16x16x32_bf16 v[40:43], v[166:169], v[216:219], v[40:43]
	v_mfma_f32_16x16x32_bf16 v[44:47], v[174:177], v[216:219], v[44:47]
	v_mfma_f32_16x16x32_bf16 v[32:35], v[166:169], v[224:227], v[32:35]
	v_mfma_f32_16x16x32_bf16 v[36:39], v[174:177], v[224:227], v[36:39]
	s_setprio 0
	s_setprio 1
	v_mfma_f32_16x16x32_bf16 v[12:15], v[178:181], v[196:199], v[12:15]
	v_mfma_f32_16x16x32_bf16 v[28:31], v[188:191], v[196:199], v[28:31]
	v_mfma_f32_16x16x32_bf16 v[8:11], v[178:181], v[204:207], v[8:11]
	v_mfma_f32_16x16x32_bf16 v[24:27], v[188:191], v[204:207], v[24:27]
	v_mfma_f32_16x16x32_bf16 v[4:7], v[178:181], v[212:215], v[4:7]
	v_mfma_f32_16x16x32_bf16 v[20:23], v[188:191], v[212:215], v[20:23]
	v_mfma_f32_16x16x32_bf16 v[0:3], v[178:181], v[220:223], v[0:3]
	v_mfma_f32_16x16x32_bf16 v[16:19], v[188:191], v[220:223], v[16:19]
	v_mfma_f32_16x16x32_bf16 v[12:15], v[184:187], v[200:203], v[12:15]
	v_mfma_f32_16x16x32_bf16 v[28:31], v[192:195], v[200:203], v[28:31]
	v_mfma_f32_16x16x32_bf16 v[8:11], v[184:187], v[208:211], v[8:11]
	v_mfma_f32_16x16x32_bf16 v[24:27], v[192:195], v[208:211], v[24:27]
	v_mfma_f32_16x16x32_bf16 v[4:7], v[184:187], v[216:219], v[4:7]
	v_mfma_f32_16x16x32_bf16 v[20:23], v[192:195], v[216:219], v[20:23]
	v_mfma_f32_16x16x32_bf16 v[0:3], v[184:187], v[224:227], v[0:3]
	v_mfma_f32_16x16x32_bf16 v[16:19], v[192:195], v[224:227], v[16:19]
	s_barrier
	s_setprio 0
	s_add_i32 s56, s56, 2
	s_add_u32 s30, s30, 0x100
	s_addc_u32 s31, s31, 0
	s_add_u32 s54, s54, 0x100
	s_addc_u32 s55, s55, 0
	s_cmp_gt_u32 s56, 61
	s_cbranch_scc0 .LBB0_1343
	s_and_b64 vcc, exec, s[16:17]
	s_cbranch_vccz .LBB0_1346
	s_barrier
